# attention classes: removed 57 canonicalising self-max ops (identity on arithmetic results) from the softmax chains
# speedup vs baseline: 1.0076x; 1.0022x over previous
; #define LAS __attribute__((address_space(3)))
; __device__ __forceinline__ float half_max(float v) { unsigned a, b; half_swap(__builtin_bit_cast(unsigned, v), a, b); return fmaxf(__builtin_bit_cast(float, a), __builtin_bit_cast(float, b)); }
; #define MFMA32(a, b, c) __builtin_amdgcn_mfma_f32_32x32x16_bf16((a), (b), (c), 0, 0, 0)
; template <int NDT, class F>
; __device__ __forceinline__ void softmax_body(f32x16& s, const F& f, int k0, int hh, f32x16 (&o)[NDT], float& m, float& l, bf16x8& pf0, bf16x8& pf1, const int MASK) {
;     float mx = NEG_BIG;
;     if (MASK == 1) {
; #pragma unroll
;         for (int r = 0; r < 16; ++r) s[r] = f.valid(k0 + CR(r) + 4 * hh) ? s[r] : NEG_BIG; }
; #pragma unroll
;     for (int r = 0; r < 16; ++r) mx = fmaxf(mx, s[r]);
;     mx = fmaf(mx, QK_SCL, f.tadd);
;     const bool on = MASK != 2 || f.lane_on();
;     mx = on ? mx : NEG_BIG;
;     mx = half_max(mx);
;     if (__ballot(mx > m) != 0ull) { const float mn = fmaxf(m, mx), alpha = __builtin_amdgcn_exp2f(m - mn); m = mn; l *= alpha;
; #pragma unroll
;         for (int dt = 0; dt < NDT; ++dt) o[dt] = o[dt] * alpha; }
; template <int NDT, bool MASK, class F>
; __device__ __forceinline__ void att_compute_lds(const bf16x8 (&qf)[4], const LAS unsigned char* cur, int fk, int fv, const F& f, int k0, int hh, f32x16 (&o)[NDT], float& m, float& l) {
;     f32x16 s;
; #pragma unroll
;     for (int ks = 0; ks < 4; ++ks) { const bf16x8 kf = *(const LAS bf16x8*)(cur + (fk ^ (ks << 5))); s = MFMA32(kf, qf[ks], ks == 0 ? f.cv : s); }
;     bf16x8 va0 = *(const LAS bf16x8*)(cur + fv), va1 = *(const LAS bf16x8*)(cur + (fv ^ 32));
;     __builtin_amdgcn_sched_barrier(0);
;     bf16x8 pf0, pf1; softmax_tile<NDT, MASK>(s, f, k0, hh, o, m, l, pf0, pf1);
.LBB0_561:
	s_add_i32 s4, s25, 0xc0
	v_add_u32_e32 v203, s25, v200
	v_cmp_lt_u32_e32 vcc, s4, v197
	s_and_saveexec_b64 s[20:21], vcc
	s_cbranch_execz .LBB0_571
	s_waitcnt lgkmcnt(0)
	ds_read_b128 v[168:171], v192 offset:4096
	ds_read_b128 v[164:167], v193 offset:4096
	ds_read_b128 v[160:163], v194 offset:4096
	ds_read_b128 v[156:159], v195 offset:4096
	ds_read_b128 v[148:151], v196 offset:24576
	ds_read_b128 v[152:155], v175 offset:24576
	v_cvt_f32_i32_e32 v84, v201
	s_movk_i32 s5, 0xea0
	v_cmp_ne_u32_e32 vcc, s5, v203
	v_mul_f32_e64 v204, -v183, v84
	s_and_saveexec_b64 s[12:13], vcc
	s_xor_b64 s[76:77], exec, s[12:13]
	s_cbranch_execz .LBB0_566
	s_waitcnt vmcnt(5) lgkmcnt(0)
	v_mfma_f32_32x32x16_bf16 v[84:99], v[168:171], v[108:111], v[68:83]
	v_mfma_f32_32x32x16_bf16 v[84:99], v[164:167], v[100:103], v[84:99]
	v_mfma_f32_32x32x16_bf16 v[84:99], v[160:163], v[104:107], v[84:99]
	s_waitcnt vmcnt(4)
	v_mfma_f32_32x32x16_bf16 v[84:99], v[156:159], v[112:115], v[84:99]
	s_nop 11
	v_max3_f32 v156, v84, s86, v85
	v_max3_f32 v156, v156, v86, v87
	v_max3_f32 v156, v156, v88, v89
	v_max3_f32 v156, v156, v90, v91
	v_max3_f32 v156, v156, v92, v93
	v_max3_f32 v156, v156, v94, v95
	v_max3_f32 v156, v156, v96, v97
	v_max3_f32 v156, v156, v98, v99
	v_fmamk_f32 v156, v156, 0x3e38aa3b, v204
	v_mov_b32_e32 v157, v156
	s_nop 1
	v_permlane32_swap_b32_e32 v156, v157
	v_max_f32_e32 v156, v156, v157
	v_cmp_gt_f32_e32 vcc, v156, v202
	s_cbranch_vccz .LBB0_565
	v_max_f32_e32 v157, v202, v202
	v_max_f32_e32 v157, v157, v156
	v_sub_f32_e32 v156, v202, v157
	v_exp_f32_e32 v156, v156
	v_mov_b32_e32 v202, v157
	v_mul_f32_e32 v187, v187, v156
	v_pk_mul_f32 v[66:67], v[66:67], v[156:157] op_sel_hi:[1,0]
	v_pk_mul_f32 v[64:65], v[64:65], v[156:157] op_sel_hi:[1,0]
	v_pk_mul_f32 v[62:63], v[62:63], v[156:157] op_sel_hi:[1,0]
	v_pk_mul_f32 v[60:61], v[60:61], v[156:157] op_sel_hi:[1,0]
	v_pk_mul_f32 v[58:59], v[58:59], v[156:157] op_sel_hi:[1,0]
	v_pk_mul_f32 v[56:57], v[56:57], v[156:157] op_sel_hi:[1,0]
	v_pk_mul_f32 v[54:55], v[54:55], v[156:157] op_sel_hi:[1,0]
	v_pk_mul_f32 v[52:53], v[52:53], v[156:157] op_sel_hi:[1,0]
	v_pk_mul_f32 v[50:51], v[50:51], v[156:157] op_sel_hi:[1,0]
	v_pk_mul_f32 v[48:49], v[48:49], v[156:157] op_sel_hi:[1,0]
	v_pk_mul_f32 v[46:47], v[46:47], v[156:157] op_sel_hi:[1,0]
	v_pk_mul_f32 v[44:45], v[44:45], v[156:157] op_sel_hi:[1,0]
	v_pk_mul_f32 v[42:43], v[42:43], v[156:157] op_sel_hi:[1,0]
	v_pk_mul_f32 v[40:41], v[40:41], v[156:157] op_sel_hi:[1,0]
	v_pk_mul_f32 v[38:39], v[38:39], v[156:157] op_sel_hi:[1,0]
	v_pk_mul_f32 v[36:37], v[36:37], v[156:157] op_sel_hi:[1,0]
	v_pk_mul_f32 v[34:35], v[34:35], v[156:157] op_sel_hi:[1,0]
	v_pk_mul_f32 v[32:33], v[32:33], v[156:157] op_sel_hi:[1,0]
	v_pk_mul_f32 v[30:31], v[30:31], v[156:157] op_sel_hi:[1,0]
	v_pk_mul_f32 v[28:29], v[28:29], v[156:157] op_sel_hi:[1,0]
	v_pk_mul_f32 v[26:27], v[26:27], v[156:157] op_sel_hi:[1,0]
	v_pk_mul_f32 v[24:25], v[24:25], v[156:157] op_sel_hi:[1,0]
	v_pk_mul_f32 v[22:23], v[22:23], v[156:157] op_sel_hi:[1,0]
	v_pk_mul_f32 v[20:21], v[20:21], v[156:157] op_sel_hi:[1,0]
	v_pk_mul_f32 v[18:19], v[18:19], v[156:157] op_sel_hi:[1,0]
	v_pk_mul_f32 v[16:17], v[16:17], v[156:157] op_sel_hi:[1,0]
	v_pk_mul_f32 v[14:15], v[14:15], v[156:157] op_sel_hi:[1,0]
	v_pk_mul_f32 v[12:13], v[12:13], v[156:157] op_sel_hi:[1,0]
	v_pk_mul_f32 v[10:11], v[10:11], v[156:157] op_sel_hi:[1,0]
	v_pk_mul_f32 v[8:9], v[8:9], v[156:157] op_sel_hi:[1,0]
	v_pk_mul_f32 v[6:7], v[6:7], v[156:157] op_sel_hi:[1,0]
	v_pk_mul_f32 v[4:5], v[4:5], v[156:157] op_sel_hi:[1,0]

; #define LAS __attribute__((address_space(3)))
; __device__ __forceinline__ float half_max(float v) { unsigned a, b; half_swap(__builtin_bit_cast(unsigned, v), a, b); return fmaxf(__builtin_bit_cast(float, a), __builtin_bit_cast(float, b)); }
; #define MFMA32(a, b, c) __builtin_amdgcn_mfma_f32_32x32x16_bf16((a), (b), (c), 0, 0, 0)
; template <int NDT, class F>
; __device__ __forceinline__ void softmax_body(f32x16& s, const F& f, int k0, int hh, f32x16 (&o)[NDT], float& m, float& l, bf16x8& pf0, bf16x8& pf1, const int MASK) {
;     float mx = NEG_BIG;
;     if (MASK == 1) {
; #pragma unroll
;         for (int r = 0; r < 16; ++r) s[r] = f.valid(k0 + CR(r) + 4 * hh) ? s[r] : NEG_BIG; }
; #pragma unroll
;     for (int r = 0; r < 16; ++r) mx = fmaxf(mx, s[r]);
;     mx = fmaf(mx, QK_SCL, f.tadd);
;     const bool on = MASK != 2 || f.lane_on();
;     mx = on ? mx : NEG_BIG;
;     mx = half_max(mx);
;     if (__ballot(mx > m) != 0ull) { const float mn = fmaxf(m, mx), alpha = __builtin_amdgcn_exp2f(m - mn); m = mn; l *= alpha;
; #pragma unroll
;         for (int dt = 0; dt < NDT; ++dt) o[dt] = o[dt] * alpha; }
; template <int NDT, bool MASK, class F>
; __device__ __forceinline__ void att_compute_lds(const bf16x8 (&qf)[4], const LAS unsigned char* cur, int fk, int fv, const F& f, int k0, int hh, f32x16 (&o)[NDT], float& m, float& l) {
;     f32x16 s;
; #pragma unroll
;     for (int ks = 0; ks < 4; ++ks) { const bf16x8 kf = *(const LAS bf16x8*)(cur + (fk ^ (ks << 5))); s = MFMA32(kf, qf[ks], ks == 0 ? f.cv : s); }
;     bf16x8 va0 = *(const LAS bf16x8*)(cur + fv), va1 = *(const LAS bf16x8*)(cur + (fv ^ 32));
;     __builtin_amdgcn_sched_barrier(0);
;     bf16x8 pf0, pf1; softmax_tile<NDT, MASK>(s, f, k0, hh, o, m, l, pf0, pf1);
.LBB0_566:
	s_andn2_saveexec_b64 s[76:77], s[76:77]
	s_cbranch_execz .LBB0_570
	s_waitcnt vmcnt(5) lgkmcnt(0)
	v_mfma_f32_32x32x16_bf16 v[84:99], v[168:171], v[108:111], v[68:83]
	v_mfma_f32_32x32x16_bf16 v[84:99], v[164:167], v[100:103], v[84:99]
	v_mfma_f32_32x32x16_bf16 v[84:99], v[160:163], v[104:107], v[84:99]
	s_waitcnt vmcnt(4)
	v_mfma_f32_32x32x16_bf16 v[84:99], v[156:159], v[112:115], v[84:99]
	s_nop 11
	v_cndmask_b32_e64 v162, v84, v235, s[38:39]
	v_cndmask_b32_e64 v163, v235, v85, s[40:41]
	v_cndmask_b32_e64 v160, v86, v235, s[42:43]
	v_cndmask_b32_e64 v161, v87, v235, s[44:45]
	v_cndmask_b32_e64 v156, v90, v235, s[50:51]
	v_cndmask_b32_e64 v90, v92, v235, s[54:55]
	v_max3_f32 v92, v162, s86, v163
	v_cndmask_b32_e64 v158, v88, v235, s[46:47]
	v_cndmask_b32_e64 v159, v89, v235, s[48:49]
	v_max3_f32 v92, v92, v160, v161
	v_cndmask_b32_e64 v157, v91, v235, s[52:53]
	v_max3_f32 v92, v92, v158, v159
	v_cndmask_b32_e64 v91, v93, v235, s[56:57]
	v_max3_f32 v92, v92, v156, v157
	v_cndmask_b32_e64 v88, v94, v235, s[58:59]
	v_cndmask_b32_e64 v89, v95, v235, s[60:61]
	v_max3_f32 v92, v92, v90, v91
	v_cndmask_b32_e64 v86, v96, v235, s[62:63]
	v_cndmask_b32_e64 v87, v97, v235, s[64:65]
	v_max3_f32 v92, v92, v88, v89
	v_cndmask_b32_e64 v84, v98, v235, s[66:67]
	v_cndmask_b32_e64 v85, v99, v235, s[68:69]
	v_max3_f32 v92, v92, v86, v87
	v_max3_f32 v92, v92, v84, v85
	v_fmamk_f32 v92, v92, 0x3e38aa3b, v204
	v_mov_b32_e32 v93, v92
	s_nop 1
	v_permlane32_swap_b32_e32 v92, v93
	v_max_f32_e32 v92, v92, v93
	v_cmp_gt_f32_e32 vcc, v92, v202
	s_cbranch_vccz .LBB0_569
	v_max_f32_e32 v93, v202, v202
	v_max_f32_e32 v93, v93, v92
	v_sub_f32_e32 v92, v202, v93
	v_exp_f32_e32 v92, v92
	v_mov_b32_e32 v202, v93
	v_mul_f32_e32 v187, v187, v92
	v_pk_mul_f32 v[66:67], v[66:67], v[92:93] op_sel_hi:[1,0]
	v_pk_mul_f32 v[64:65], v[64:65], v[92:93] op_sel_hi:[1,0]
	v_pk_mul_f32 v[62:63], v[62:63], v[92:93] op_sel_hi:[1,0]
	v_pk_mul_f32 v[60:61], v[60:61], v[92:93] op_sel_hi:[1,0]
	v_pk_mul_f32 v[58:59], v[58:59], v[92:93] op_sel_hi:[1,0]
	v_pk_mul_f32 v[56:57], v[56:57], v[92:93] op_sel_hi:[1,0]
	v_pk_mul_f32 v[54:55], v[54:55], v[92:93] op_sel_hi:[1,0]
	v_pk_mul_f32 v[52:53], v[52:53], v[92:93] op_sel_hi:[1,0]
	v_pk_mul_f32 v[50:51], v[50:51], v[92:93] op_sel_hi:[1,0]
	v_pk_mul_f32 v[48:49], v[48:49], v[92:93] op_sel_hi:[1,0]
	v_pk_mul_f32 v[46:47], v[46:47], v[92:93] op_sel_hi:[1,0]
	v_pk_mul_f32 v[44:45], v[44:45], v[92:93] op_sel_hi:[1,0]
	v_pk_mul_f32 v[42:43], v[42:43], v[92:93] op_sel_hi:[1,0]
	v_pk_mul_f32 v[40:41], v[40:41], v[92:93] op_sel_hi:[1,0]
	v_pk_mul_f32 v[38:39], v[38:39], v[92:93] op_sel_hi:[1,0]
	v_pk_mul_f32 v[36:37], v[36:37], v[92:93] op_sel_hi:[1,0]
	v_pk_mul_f32 v[34:35], v[34:35], v[92:93] op_sel_hi:[1,0]
	v_pk_mul_f32 v[32:33], v[32:33], v[92:93] op_sel_hi:[1,0]
	v_pk_mul_f32 v[30:31], v[30:31], v[92:93] op_sel_hi:[1,0]
	v_pk_mul_f32 v[28:29], v[28:29], v[92:93] op_sel_hi:[1,0]
	v_pk_mul_f32 v[26:27], v[26:27], v[92:93] op_sel_hi:[1,0]
	v_pk_mul_f32 v[24:25], v[24:25], v[92:93] op_sel_hi:[1,0]
	v_pk_mul_f32 v[22:23], v[22:23], v[92:93] op_sel_hi:[1,0]
	v_pk_mul_f32 v[20:21], v[20:21], v[92:93] op_sel_hi:[1,0]
	v_pk_mul_f32 v[18:19], v[18:19], v[92:93] op_sel_hi:[1,0]
	v_pk_mul_f32 v[16:17], v[16:17], v[92:93] op_sel_hi:[1,0]
	v_pk_mul_f32 v[14:15], v[14:15], v[92:93] op_sel_hi:[1,0]
	v_pk_mul_f32 v[12:13], v[12:13], v[92:93] op_sel_hi:[1,0]
	v_pk_mul_f32 v[10:11], v[10:11], v[92:93] op_sel_hi:[1,0]
	v_pk_mul_f32 v[8:9], v[8:9], v[92:93] op_sel_hi:[1,0]
	v_pk_mul_f32 v[6:7], v[6:7], v[92:93] op_sel_hi:[1,0]
	v_pk_mul_f32 v[4:5], v[4:5], v[92:93] op_sel_hi:[1,0]

; #define LAS __attribute__((address_space(3)))
; __device__ __forceinline__ float half_max(float v) { unsigned a, b; half_swap(__builtin_bit_cast(unsigned, v), a, b); return fmaxf(__builtin_bit_cast(float, a), __builtin_bit_cast(float, b)); }
; #define MFMA32(a, b, c) __builtin_amdgcn_mfma_f32_32x32x16_bf16((a), (b), (c), 0, 0, 0)
; template <int NDT, class F>
; __device__ __forceinline__ void softmax_body(f32x16& s, const F& f, int k0, int hh, f32x16 (&o)[NDT], float& m, float& l, bf16x8& pf0, bf16x8& pf1, const int MASK) {
;     float mx = NEG_BIG;
;     if (MASK == 1) {
; #pragma unroll
;         for (int r = 0; r < 16; ++r) s[r] = f.valid(k0 + CR(r) + 4 * hh) ? s[r] : NEG_BIG; }
; #pragma unroll
;     for (int r = 0; r < 16; ++r) mx = fmaxf(mx, s[r]);
;     mx = fmaf(mx, QK_SCL, f.tadd);
;     const bool on = MASK != 2 || f.lane_on();
;     mx = on ? mx : NEG_BIG;
;     mx = half_max(mx);
;     if (__ballot(mx > m) != 0ull) { const float mn = fmaxf(m, mx), alpha = __builtin_amdgcn_exp2f(m - mn); m = mn; l *= alpha;
; #pragma unroll
;         for (int dt = 0; dt < NDT; ++dt) o[dt] = o[dt] * alpha; }
; template <int NDT, bool MASK, class F>
; __device__ __forceinline__ void att_compute_lds(const bf16x8 (&qf)[4], const LAS unsigned char* cur, int fk, int fv, const F& f, int k0, int hh, f32x16 (&o)[NDT], float& m, float& l) {
;     f32x16 s;
; #pragma unroll
;     for (int ks = 0; ks < 4; ++ks) { const bf16x8 kf = *(const LAS bf16x8*)(cur + (fk ^ (ks << 5))); s = MFMA32(kf, qf[ks], ks == 0 ? f.cv : s); }
;     bf16x8 va0 = *(const LAS bf16x8*)(cur + fv), va1 = *(const LAS bf16x8*)(cur + (fv ^ 32));
;     __builtin_amdgcn_sched_barrier(0);
;     bf16x8 pf0, pf1; softmax_tile<NDT, MASK>(s, f, k0, hh, o, m, l, pf0, pf1);
.LBB0_571:
	s_or_b64 exec, exec, s[20:21]
	v_cmp_le_u32_e32 vcc, s4, v197
	s_and_saveexec_b64 s[20:21], vcc
	s_cbranch_execz .LBB0_581
	s_waitcnt lgkmcnt(0)
	ds_read_b128 v[168:171], v192
	ds_read_b128 v[164:167], v193
	ds_read_b128 v[160:163], v194
	ds_read_b128 v[156:159], v195
	ds_read_b128 v[148:151], v196 offset:16384
	ds_read_b128 v[152:155], v175 offset:16384
	v_add_u32_e32 v84, 32, v201
	v_cvt_f32_u32_e32 v84, v84
	s_movk_i32 s4, 0xec0
	v_cmp_ne_u32_e32 vcc, s4, v203
	v_mul_f32_e64 v204, -v183, v84
	s_and_saveexec_b64 s[4:5], vcc
	s_xor_b64 s[76:77], exec, s[4:5]
	s_cbranch_execz .LBB0_576
	s_waitcnt vmcnt(5) lgkmcnt(5)
	v_mfma_f32_32x32x16_bf16 v[84:99], v[168:171], v[108:111], v[68:83]
	s_waitcnt lgkmcnt(4)
	v_mfma_f32_32x32x16_bf16 v[84:99], v[164:167], v[100:103], v[84:99]
	s_waitcnt lgkmcnt(3)
	v_mfma_f32_32x32x16_bf16 v[84:99], v[160:163], v[104:107], v[84:99]
	s_waitcnt vmcnt(4) lgkmcnt(2)
	v_mfma_f32_32x32x16_bf16 v[84:99], v[156:159], v[112:115], v[84:99]
	s_nop 11
	v_max3_f32 v156, v84, s86, v85
	v_max3_f32 v156, v156, v86, v87
	v_max3_f32 v156, v156, v88, v89
	v_max3_f32 v156, v156, v90, v91
	v_max3_f32 v156, v156, v92, v93
	v_max3_f32 v156, v156, v94, v95
	v_max3_f32 v156, v156, v96, v97
	v_max3_f32 v156, v156, v98, v99
	v_fmamk_f32 v156, v156, 0x3e38aa3b, v204
	v_mov_b32_e32 v157, v156
	s_nop 1
	v_permlane32_swap_b32_e32 v156, v157
	v_max_f32_e32 v156, v156, v157
	v_cmp_gt_f32_e32 vcc, v156, v202
	s_cbranch_vccz .LBB0_575
	v_max_f32_e32 v157, v202, v202
	v_max_f32_e32 v157, v157, v156
	v_sub_f32_e32 v156, v202, v157
	v_exp_f32_e32 v156, v156
	v_mov_b32_e32 v202, v157
	v_mul_f32_e32 v187, v187, v156
	v_pk_mul_f32 v[66:67], v[66:67], v[156:157] op_sel_hi:[1,0]
	v_pk_mul_f32 v[64:65], v[64:65], v[156:157] op_sel_hi:[1,0]
	v_pk_mul_f32 v[62:63], v[62:63], v[156:157] op_sel_hi:[1,0]
	v_pk_mul_f32 v[60:61], v[60:61], v[156:157] op_sel_hi:[1,0]
	v_pk_mul_f32 v[58:59], v[58:59], v[156:157] op_sel_hi:[1,0]
	v_pk_mul_f32 v[56:57], v[56:57], v[156:157] op_sel_hi:[1,0]
	v_pk_mul_f32 v[54:55], v[54:55], v[156:157] op_sel_hi:[1,0]
	v_pk_mul_f32 v[52:53], v[52:53], v[156:157] op_sel_hi:[1,0]
	v_pk_mul_f32 v[50:51], v[50:51], v[156:157] op_sel_hi:[1,0]
	v_pk_mul_f32 v[48:49], v[48:49], v[156:157] op_sel_hi:[1,0]
	v_pk_mul_f32 v[46:47], v[46:47], v[156:157] op_sel_hi:[1,0]
	v_pk_mul_f32 v[44:45], v[44:45], v[156:157] op_sel_hi:[1,0]
	v_pk_mul_f32 v[42:43], v[42:43], v[156:157] op_sel_hi:[1,0]
	v_pk_mul_f32 v[40:41], v[40:41], v[156:157] op_sel_hi:[1,0]
	v_pk_mul_f32 v[38:39], v[38:39], v[156:157] op_sel_hi:[1,0]
	v_pk_mul_f32 v[36:37], v[36:37], v[156:157] op_sel_hi:[1,0]
	v_pk_mul_f32 v[34:35], v[34:35], v[156:157] op_sel_hi:[1,0]
	v_pk_mul_f32 v[32:33], v[32:33], v[156:157] op_sel_hi:[1,0]
	v_pk_mul_f32 v[30:31], v[30:31], v[156:157] op_sel_hi:[1,0]
	v_pk_mul_f32 v[28:29], v[28:29], v[156:157] op_sel_hi:[1,0]
	v_pk_mul_f32 v[26:27], v[26:27], v[156:157] op_sel_hi:[1,0]
	v_pk_mul_f32 v[24:25], v[24:25], v[156:157] op_sel_hi:[1,0]
	v_pk_mul_f32 v[22:23], v[22:23], v[156:157] op_sel_hi:[1,0]
	v_pk_mul_f32 v[20:21], v[20:21], v[156:157] op_sel_hi:[1,0]
	v_pk_mul_f32 v[18:19], v[18:19], v[156:157] op_sel_hi:[1,0]
	v_pk_mul_f32 v[16:17], v[16:17], v[156:157] op_sel_hi:[1,0]
	v_pk_mul_f32 v[14:15], v[14:15], v[156:157] op_sel_hi:[1,0]
	v_pk_mul_f32 v[12:13], v[12:13], v[156:157] op_sel_hi:[1,0]
	v_pk_mul_f32 v[10:11], v[10:11], v[156:157] op_sel_hi:[1,0]
	v_pk_mul_f32 v[8:9], v[8:9], v[156:157] op_sel_hi:[1,0]
	v_pk_mul_f32 v[6:7], v[6:7], v[156:157] op_sel_hi:[1,0]
	v_pk_mul_f32 v[4:5], v[4:5], v[156:157] op_sel_hi:[1,0]

; #define LAS __attribute__((address_space(3)))
; __device__ __forceinline__ float half_max(float v) { unsigned a, b; half_swap(__builtin_bit_cast(unsigned, v), a, b); return fmaxf(__builtin_bit_cast(float, a), __builtin_bit_cast(float, b)); }
; #define MFMA32(a, b, c) __builtin_amdgcn_mfma_f32_32x32x16_bf16((a), (b), (c), 0, 0, 0)
; template <int NDT, class F>
; __device__ __forceinline__ void softmax_body(f32x16& s, const F& f, int k0, int hh, f32x16 (&o)[NDT], float& m, float& l, bf16x8& pf0, bf16x8& pf1, const int MASK) {
;     float mx = NEG_BIG;
;     if (MASK == 1) {
; #pragma unroll
;         for (int r = 0; r < 16; ++r) s[r] = f.valid(k0 + CR(r) + 4 * hh) ? s[r] : NEG_BIG; }
; #pragma unroll
;     for (int r = 0; r < 16; ++r) mx = fmaxf(mx, s[r]);
;     mx = fmaf(mx, QK_SCL, f.tadd);
;     const bool on = MASK != 2 || f.lane_on();
;     mx = on ? mx : NEG_BIG;
;     mx = half_max(mx);
;     if (__ballot(mx > m) != 0ull) { const float mn = fmaxf(m, mx), alpha = __builtin_amdgcn_exp2f(m - mn); m = mn; l *= alpha;
; #pragma unroll
;         for (int dt = 0; dt < NDT; ++dt) o[dt] = o[dt] * alpha; }
; template <int NDT, bool MASK, class F>
; __device__ __forceinline__ void att_compute_lds(const bf16x8 (&qf)[4], const LAS unsigned char* cur, int fk, int fv, const F& f, int k0, int hh, f32x16 (&o)[NDT], float& m, float& l) {
;     f32x16 s;
; #pragma unroll
;     for (int ks = 0; ks < 4; ++ks) { const bf16x8 kf = *(const LAS bf16x8*)(cur + (fk ^ (ks << 5))); s = MFMA32(kf, qf[ks], ks == 0 ? f.cv : s); }
;     bf16x8 va0 = *(const LAS bf16x8*)(cur + fv), va1 = *(const LAS bf16x8*)(cur + (fv ^ 32));
;     __builtin_amdgcn_sched_barrier(0);
;     bf16x8 pf0, pf1; softmax_tile<NDT, MASK>(s, f, k0, hh, o, m, l, pf0, pf1);
.LBB0_576:
	s_andn2_saveexec_b64 s[76:77], s[76:77]
	s_cbranch_execz .LBB0_580
	s_waitcnt vmcnt(5) lgkmcnt(5)
	v_mfma_f32_32x32x16_bf16 v[84:99], v[168:171], v[108:111], v[68:83]
	s_waitcnt lgkmcnt(4)
	v_mfma_f32_32x32x16_bf16 v[84:99], v[164:167], v[100:103], v[84:99]
	s_waitcnt lgkmcnt(3)
	v_mfma_f32_32x32x16_bf16 v[84:99], v[160:163], v[104:107], v[84:99]
	s_waitcnt vmcnt(4) lgkmcnt(2)
	v_mfma_f32_32x32x16_bf16 v[84:99], v[156:159], v[112:115], v[84:99]
	s_nop 11
	v_cndmask_b32_e64 v162, v84, v235, s[38:39]
	v_cndmask_b32_e64 v163, v235, v85, s[40:41]
	v_cndmask_b32_e64 v160, v86, v235, s[42:43]
	v_cndmask_b32_e64 v161, v87, v235, s[44:45]
	v_cndmask_b32_e64 v156, v90, v235, s[50:51]
	v_cndmask_b32_e64 v90, v92, v235, s[54:55]
	v_max3_f32 v92, v162, s86, v163
	v_cndmask_b32_e64 v158, v88, v235, s[46:47]
	v_cndmask_b32_e64 v159, v89, v235, s[48:49]
	v_max3_f32 v92, v92, v160, v161
	v_cndmask_b32_e64 v157, v91, v235, s[52:53]
	v_max3_f32 v92, v92, v158, v159
	v_cndmask_b32_e64 v91, v93, v235, s[56:57]
	v_max3_f32 v92, v92, v156, v157
	v_cndmask_b32_e64 v88, v94, v235, s[58:59]
	v_cndmask_b32_e64 v89, v95, v235, s[60:61]
	v_max3_f32 v92, v92, v90, v91
	v_cndmask_b32_e64 v86, v96, v235, s[62:63]
	v_cndmask_b32_e64 v87, v97, v235, s[64:65]
	v_max3_f32 v92, v92, v88, v89
	v_cndmask_b32_e64 v84, v98, v235, s[66:67]
	v_cndmask_b32_e64 v85, v99, v235, s[68:69]
	v_max3_f32 v92, v92, v86, v87
	v_max3_f32 v92, v92, v84, v85
	v_fmamk_f32 v92, v92, 0x3e38aa3b, v204
	v_mov_b32_e32 v93, v92
	s_nop 1
	v_permlane32_swap_b32_e32 v92, v93
	v_max_f32_e32 v92, v92, v93
	v_cmp_gt_f32_e32 vcc, v92, v202
	s_cbranch_vccz .LBB0_579
	v_max_f32_e32 v93, v202, v202
	v_max_f32_e32 v93, v93, v92
	v_sub_f32_e32 v92, v202, v93
	v_exp_f32_e32 v92, v92
	v_mov_b32_e32 v202, v93
	v_mul_f32_e32 v187, v187, v92
	v_pk_mul_f32 v[66:67], v[66:67], v[92:93] op_sel_hi:[1,0]
	v_pk_mul_f32 v[64:65], v[64:65], v[92:93] op_sel_hi:[1,0]
	v_pk_mul_f32 v[62:63], v[62:63], v[92:93] op_sel_hi:[1,0]
	v_pk_mul_f32 v[60:61], v[60:61], v[92:93] op_sel_hi:[1,0]
	v_pk_mul_f32 v[58:59], v[58:59], v[92:93] op_sel_hi:[1,0]
	v_pk_mul_f32 v[56:57], v[56:57], v[92:93] op_sel_hi:[1,0]
	v_pk_mul_f32 v[54:55], v[54:55], v[92:93] op_sel_hi:[1,0]
	v_pk_mul_f32 v[52:53], v[52:53], v[92:93] op_sel_hi:[1,0]
	v_pk_mul_f32 v[50:51], v[50:51], v[92:93] op_sel_hi:[1,0]
	v_pk_mul_f32 v[48:49], v[48:49], v[92:93] op_sel_hi:[1,0]
	v_pk_mul_f32 v[46:47], v[46:47], v[92:93] op_sel_hi:[1,0]
	v_pk_mul_f32 v[44:45], v[44:45], v[92:93] op_sel_hi:[1,0]
	v_pk_mul_f32 v[42:43], v[42:43], v[92:93] op_sel_hi:[1,0]
	v_pk_mul_f32 v[40:41], v[40:41], v[92:93] op_sel_hi:[1,0]
	v_pk_mul_f32 v[38:39], v[38:39], v[92:93] op_sel_hi:[1,0]
	v_pk_mul_f32 v[36:37], v[36:37], v[92:93] op_sel_hi:[1,0]
	v_pk_mul_f32 v[34:35], v[34:35], v[92:93] op_sel_hi:[1,0]
	v_pk_mul_f32 v[32:33], v[32:33], v[92:93] op_sel_hi:[1,0]
	v_pk_mul_f32 v[30:31], v[30:31], v[92:93] op_sel_hi:[1,0]
	v_pk_mul_f32 v[28:29], v[28:29], v[92:93] op_sel_hi:[1,0]
	v_pk_mul_f32 v[26:27], v[26:27], v[92:93] op_sel_hi:[1,0]
	v_pk_mul_f32 v[24:25], v[24:25], v[92:93] op_sel_hi:[1,0]
	v_pk_mul_f32 v[22:23], v[22:23], v[92:93] op_sel_hi:[1,0]
	v_pk_mul_f32 v[20:21], v[20:21], v[92:93] op_sel_hi:[1,0]
	v_pk_mul_f32 v[18:19], v[18:19], v[92:93] op_sel_hi:[1,0]
	v_pk_mul_f32 v[16:17], v[16:17], v[92:93] op_sel_hi:[1,0]
	v_pk_mul_f32 v[14:15], v[14:15], v[92:93] op_sel_hi:[1,0]
	v_pk_mul_f32 v[12:13], v[12:13], v[92:93] op_sel_hi:[1,0]
	v_pk_mul_f32 v[10:11], v[10:11], v[92:93] op_sel_hi:[1,0]
	v_pk_mul_f32 v[8:9], v[8:9], v[92:93] op_sel_hi:[1,0]
	v_pk_mul_f32 v[6:7], v[6:7], v[92:93] op_sel_hi:[1,0]
	v_pk_mul_f32 v[4:5], v[4:5], v[92:93] op_sel_hi:[1,0]

; #define LAS __attribute__((address_space(3)))
; __device__ __forceinline__ float half_max(float v) { unsigned a, b; half_swap(__builtin_bit_cast(unsigned, v), a, b); return fmaxf(__builtin_bit_cast(float, a), __builtin_bit_cast(float, b)); }
; #define MFMA32(a, b, c) __builtin_amdgcn_mfma_f32_32x32x16_bf16((a), (b), (c), 0, 0, 0)
; template <int NDT, class F>
; __device__ __forceinline__ void softmax_body(f32x16& s, const F& f, int k0, int hh, f32x16 (&o)[NDT], float& m, float& l, bf16x8& pf0, bf16x8& pf1, const int MASK) {
;     float mx = NEG_BIG;
;     if (MASK == 1) {
; #pragma unroll
;         for (int r = 0; r < 16; ++r) s[r] = f.valid(k0 + CR(r) + 4 * hh) ? s[r] : NEG_BIG; }
; #pragma unroll
;     for (int r = 0; r < 16; ++r) mx = fmaxf(mx, s[r]);
;     mx = fmaf(mx, QK_SCL, f.tadd);
;     const bool on = MASK != 2 || f.lane_on();
;     mx = on ? mx : NEG_BIG;
;     mx = half_max(mx);
;     if (__ballot(mx > m) != 0ull) { const float mn = fmaxf(m, mx), alpha = __builtin_amdgcn_exp2f(m - mn); m = mn; l *= alpha;
; #pragma unroll
;         for (int dt = 0; dt < NDT; ++dt) o[dt] = o[dt] * alpha; }
; template <int NDT, bool MASK, class F>
; __device__ __forceinline__ void att_compute_lds(const bf16x8 (&qf)[4], const LAS unsigned char* cur, int fk, int fv, const F& f, int k0, int hh, f32x16 (&o)[NDT], float& m, float& l) {
;     f32x16 s;
; #pragma unroll
;     for (int ks = 0; ks < 4; ++ks) { const bf16x8 kf = *(const LAS bf16x8*)(cur + (fk ^ (ks << 5))); s = MFMA32(kf, qf[ks], ks == 0 ? f.cv : s); }
;     bf16x8 va0 = *(const LAS bf16x8*)(cur + fv), va1 = *(const LAS bf16x8*)(cur + (fv ^ 32));
;     __builtin_amdgcn_sched_barrier(0);
;     bf16x8 pf0, pf1; softmax_tile<NDT, MASK>(s, f, k0, hh, o, m, l, pf0, pf1);
.LBB0_586:
	s_add_i32 s4, s25, 0xa0
	v_cmp_le_i32_e32 vcc, s4, v197
	s_and_saveexec_b64 s[20:21], vcc
	s_cbranch_execz .LBB0_596
	s_waitcnt lgkmcnt(0)
	ds_read_b128 v[168:171], v192 offset:36864
	ds_read_b128 v[164:167], v193 offset:36864
	ds_read_b128 v[160:163], v194 offset:36864
	ds_read_b128 v[156:159], v195 offset:36864
	ds_read_b128 v[148:151], v196 offset:57344
	ds_read_b128 v[152:155], v175 offset:57344
	v_add_u32_e32 v84, 64, v201
	v_cvt_f32_i32_e32 v84, v84
	s_movk_i32 s4, 0xee0
	v_cmp_ne_u32_e32 vcc, s4, v203
	v_mul_f32_e64 v204, -v183, v84
	s_and_saveexec_b64 s[4:5], vcc
	s_xor_b64 s[76:77], exec, s[4:5]
	s_cbranch_execz .LBB0_591
	s_waitcnt vmcnt(5) lgkmcnt(5)
	v_mfma_f32_32x32x16_bf16 v[84:99], v[168:171], v[108:111], v[68:83]
	s_waitcnt lgkmcnt(4)
	v_mfma_f32_32x32x16_bf16 v[84:99], v[164:167], v[100:103], v[84:99]
	s_waitcnt lgkmcnt(3)
	v_mfma_f32_32x32x16_bf16 v[84:99], v[160:163], v[104:107], v[84:99]
	s_waitcnt vmcnt(4) lgkmcnt(2)
	v_mfma_f32_32x32x16_bf16 v[84:99], v[156:159], v[112:115], v[84:99]
	s_nop 11
	v_max3_f32 v156, v84, s86, v85
	v_max3_f32 v156, v156, v86, v87
	v_max3_f32 v156, v156, v88, v89
	v_max3_f32 v156, v156, v90, v91
	v_max3_f32 v156, v156, v92, v93
	v_max3_f32 v156, v156, v94, v95
	v_max3_f32 v156, v156, v96, v97
	v_max3_f32 v156, v156, v98, v99
	v_fmamk_f32 v156, v156, 0x3e38aa3b, v204
	v_mov_b32_e32 v157, v156
	s_nop 1
	v_permlane32_swap_b32_e32 v156, v157
	v_max_f32_e32 v156, v156, v157
	v_cmp_gt_f32_e32 vcc, v156, v202
	s_cbranch_vccz .LBB0_590
	v_max_f32_e32 v157, v202, v202
	v_max_f32_e32 v157, v157, v156
	v_sub_f32_e32 v156, v202, v157
	v_exp_f32_e32 v156, v156
	v_mov_b32_e32 v202, v157
	v_mul_f32_e32 v187, v187, v156
	v_pk_mul_f32 v[66:67], v[66:67], v[156:157] op_sel_hi:[1,0]
	v_pk_mul_f32 v[64:65], v[64:65], v[156:157] op_sel_hi:[1,0]
	v_pk_mul_f32 v[62:63], v[62:63], v[156:157] op_sel_hi:[1,0]
	v_pk_mul_f32 v[60:61], v[60:61], v[156:157] op_sel_hi:[1,0]
	v_pk_mul_f32 v[58:59], v[58:59], v[156:157] op_sel_hi:[1,0]
	v_pk_mul_f32 v[56:57], v[56:57], v[156:157] op_sel_hi:[1,0]
	v_pk_mul_f32 v[54:55], v[54:55], v[156:157] op_sel_hi:[1,0]
	v_pk_mul_f32 v[52:53], v[52:53], v[156:157] op_sel_hi:[1,0]
	v_pk_mul_f32 v[50:51], v[50:51], v[156:157] op_sel_hi:[1,0]
	v_pk_mul_f32 v[48:49], v[48:49], v[156:157] op_sel_hi:[1,0]
	v_pk_mul_f32 v[46:47], v[46:47], v[156:157] op_sel_hi:[1,0]
	v_pk_mul_f32 v[44:45], v[44:45], v[156:157] op_sel_hi:[1,0]
	v_pk_mul_f32 v[42:43], v[42:43], v[156:157] op_sel_hi:[1,0]
	v_pk_mul_f32 v[40:41], v[40:41], v[156:157] op_sel_hi:[1,0]
	v_pk_mul_f32 v[38:39], v[38:39], v[156:157] op_sel_hi:[1,0]
	v_pk_mul_f32 v[36:37], v[36:37], v[156:157] op_sel_hi:[1,0]
	v_pk_mul_f32 v[34:35], v[34:35], v[156:157] op_sel_hi:[1,0]
	v_pk_mul_f32 v[32:33], v[32:33], v[156:157] op_sel_hi:[1,0]
	v_pk_mul_f32 v[30:31], v[30:31], v[156:157] op_sel_hi:[1,0]
	v_pk_mul_f32 v[28:29], v[28:29], v[156:157] op_sel_hi:[1,0]
	v_pk_mul_f32 v[26:27], v[26:27], v[156:157] op_sel_hi:[1,0]
	v_pk_mul_f32 v[24:25], v[24:25], v[156:157] op_sel_hi:[1,0]
	v_pk_mul_f32 v[22:23], v[22:23], v[156:157] op_sel_hi:[1,0]
	v_pk_mul_f32 v[20:21], v[20:21], v[156:157] op_sel_hi:[1,0]
	v_pk_mul_f32 v[18:19], v[18:19], v[156:157] op_sel_hi:[1,0]
	v_pk_mul_f32 v[16:17], v[16:17], v[156:157] op_sel_hi:[1,0]
	v_pk_mul_f32 v[14:15], v[14:15], v[156:157] op_sel_hi:[1,0]
	v_pk_mul_f32 v[12:13], v[12:13], v[156:157] op_sel_hi:[1,0]
	v_pk_mul_f32 v[10:11], v[10:11], v[156:157] op_sel_hi:[1,0]
	v_pk_mul_f32 v[8:9], v[8:9], v[156:157] op_sel_hi:[1,0]
	v_pk_mul_f32 v[6:7], v[6:7], v[156:157] op_sel_hi:[1,0]
	v_pk_mul_f32 v[4:5], v[4:5], v[156:157] op_sel_hi:[1,0]

; #define LAS __attribute__((address_space(3)))
; __device__ __forceinline__ float half_max(float v) { unsigned a, b; half_swap(__builtin_bit_cast(unsigned, v), a, b); return fmaxf(__builtin_bit_cast(float, a), __builtin_bit_cast(float, b)); }
; #define MFMA32(a, b, c) __builtin_amdgcn_mfma_f32_32x32x16_bf16((a), (b), (c), 0, 0, 0)
; template <int NDT, class F>
; __device__ __forceinline__ void softmax_body(f32x16& s, const F& f, int k0, int hh, f32x16 (&o)[NDT], float& m, float& l, bf16x8& pf0, bf16x8& pf1, const int MASK) {
;     float mx = NEG_BIG;
;     if (MASK == 1) {
; #pragma unroll
;         for (int r = 0; r < 16; ++r) s[r] = f.valid(k0 + CR(r) + 4 * hh) ? s[r] : NEG_BIG; }
; #pragma unroll
;     for (int r = 0; r < 16; ++r) mx = fmaxf(mx, s[r]);
;     mx = fmaf(mx, QK_SCL, f.tadd);
;     const bool on = MASK != 2 || f.lane_on();
;     mx = on ? mx : NEG_BIG;
;     mx = half_max(mx);
;     if (__ballot(mx > m) != 0ull) { const float mn = fmaxf(m, mx), alpha = __builtin_amdgcn_exp2f(m - mn); m = mn; l *= alpha;
; #pragma unroll
;         for (int dt = 0; dt < NDT; ++dt) o[dt] = o[dt] * alpha; }
; template <int NDT, bool MASK, class F>
; __device__ __forceinline__ void att_compute_lds(const bf16x8 (&qf)[4], const LAS unsigned char* cur, int fk, int fv, const F& f, int k0, int hh, f32x16 (&o)[NDT], float& m, float& l) {
;     f32x16 s;
; #pragma unroll
;     for (int ks = 0; ks < 4; ++ks) { const bf16x8 kf = *(const LAS bf16x8*)(cur + (fk ^ (ks << 5))); s = MFMA32(kf, qf[ks], ks == 0 ? f.cv : s); }
;     bf16x8 va0 = *(const LAS bf16x8*)(cur + fv), va1 = *(const LAS bf16x8*)(cur + (fv ^ 32));
;     __builtin_amdgcn_sched_barrier(0);
;     bf16x8 pf0, pf1; softmax_tile<NDT, MASK>(s, f, k0, hh, o, m, l, pf0, pf1);
.LBB0_596:
	s_or_b64 exec, exec, s[20:21]
	s_add_i32 s4, s25, 0x80
	v_cmp_le_i32_e32 vcc, s4, v197
	s_and_saveexec_b64 s[20:21], vcc
	s_cbranch_execz .LBB0_606
	s_waitcnt lgkmcnt(0)
	ds_read_b128 v[168:171], v192 offset:32768
	ds_read_b128 v[164:167], v193 offset:32768
	ds_read_b128 v[160:163], v194 offset:32768
	ds_read_b128 v[156:159], v195 offset:32768
	ds_read_b128 v[148:151], v196 offset:49152
	ds_read_b128 v[152:155], v175 offset:49152
	v_add_u32_e32 v84, 0x60, v201
	v_cvt_f32_i32_e32 v84, v84
	s_movk_i32 s4, 0xf00
	v_cmp_ne_u32_e32 vcc, s4, v203
	v_mul_f32_e64 v204, -v183, v84
	s_and_saveexec_b64 s[4:5], vcc
	s_xor_b64 s[76:77], exec, s[4:5]
	s_cbranch_execz .LBB0_601
	s_waitcnt vmcnt(5) lgkmcnt(5)
	v_mfma_f32_32x32x16_bf16 v[84:99], v[168:171], v[108:111], v[68:83]
	s_waitcnt lgkmcnt(4)
	v_mfma_f32_32x32x16_bf16 v[84:99], v[164:167], v[100:103], v[84:99]
	s_waitcnt lgkmcnt(3)
	v_mfma_f32_32x32x16_bf16 v[84:99], v[160:163], v[104:107], v[84:99]
	s_waitcnt vmcnt(4) lgkmcnt(2)
	v_mfma_f32_32x32x16_bf16 v[84:99], v[156:159], v[112:115], v[84:99]
	s_nop 11
	v_max3_f32 v156, v84, s86, v85
	v_max3_f32 v156, v156, v86, v87
	v_max3_f32 v156, v156, v88, v89
	v_max3_f32 v156, v156, v90, v91
	v_max3_f32 v156, v156, v92, v93
	v_max3_f32 v156, v156, v94, v95
	v_max3_f32 v156, v156, v96, v97
	v_max3_f32 v156, v156, v98, v99
	v_fmamk_f32 v156, v156, 0x3e38aa3b, v204
	v_mov_b32_e32 v157, v156
	s_nop 1
	v_permlane32_swap_b32_e32 v156, v157
	v_max_f32_e32 v156, v156, v157
	v_cmp_gt_f32_e32 vcc, v156, v202
	s_cbranch_vccz .LBB0_600
	v_max_f32_e32 v157, v202, v202
	v_max_f32_e32 v157, v157, v156
	v_sub_f32_e32 v156, v202, v157
	v_exp_f32_e32 v156, v156
	v_mov_b32_e32 v202, v157
	v_mul_f32_e32 v187, v187, v156
	v_pk_mul_f32 v[66:67], v[66:67], v[156:157] op_sel_hi:[1,0]
	v_pk_mul_f32 v[64:65], v[64:65], v[156:157] op_sel_hi:[1,0]
	v_pk_mul_f32 v[62:63], v[62:63], v[156:157] op_sel_hi:[1,0]
	v_pk_mul_f32 v[60:61], v[60:61], v[156:157] op_sel_hi:[1,0]
	v_pk_mul_f32 v[58:59], v[58:59], v[156:157] op_sel_hi:[1,0]
	v_pk_mul_f32 v[56:57], v[56:57], v[156:157] op_sel_hi:[1,0]
	v_pk_mul_f32 v[54:55], v[54:55], v[156:157] op_sel_hi:[1,0]
	v_pk_mul_f32 v[52:53], v[52:53], v[156:157] op_sel_hi:[1,0]
	v_pk_mul_f32 v[50:51], v[50:51], v[156:157] op_sel_hi:[1,0]
	v_pk_mul_f32 v[48:49], v[48:49], v[156:157] op_sel_hi:[1,0]
	v_pk_mul_f32 v[46:47], v[46:47], v[156:157] op_sel_hi:[1,0]
	v_pk_mul_f32 v[44:45], v[44:45], v[156:157] op_sel_hi:[1,0]
	v_pk_mul_f32 v[42:43], v[42:43], v[156:157] op_sel_hi:[1,0]
	v_pk_mul_f32 v[40:41], v[40:41], v[156:157] op_sel_hi:[1,0]
	v_pk_mul_f32 v[38:39], v[38:39], v[156:157] op_sel_hi:[1,0]
	v_pk_mul_f32 v[36:37], v[36:37], v[156:157] op_sel_hi:[1,0]
	v_pk_mul_f32 v[34:35], v[34:35], v[156:157] op_sel_hi:[1,0]
	v_pk_mul_f32 v[32:33], v[32:33], v[156:157] op_sel_hi:[1,0]
	v_pk_mul_f32 v[30:31], v[30:31], v[156:157] op_sel_hi:[1,0]
	v_pk_mul_f32 v[28:29], v[28:29], v[156:157] op_sel_hi:[1,0]
	v_pk_mul_f32 v[26:27], v[26:27], v[156:157] op_sel_hi:[1,0]
	v_pk_mul_f32 v[24:25], v[24:25], v[156:157] op_sel_hi:[1,0]
	v_pk_mul_f32 v[22:23], v[22:23], v[156:157] op_sel_hi:[1,0]
	v_pk_mul_f32 v[20:21], v[20:21], v[156:157] op_sel_hi:[1,0]
	v_pk_mul_f32 v[18:19], v[18:19], v[156:157] op_sel_hi:[1,0]
	v_pk_mul_f32 v[16:17], v[16:17], v[156:157] op_sel_hi:[1,0]
	v_pk_mul_f32 v[14:15], v[14:15], v[156:157] op_sel_hi:[1,0]
	v_pk_mul_f32 v[12:13], v[12:13], v[156:157] op_sel_hi:[1,0]
	v_pk_mul_f32 v[10:11], v[10:11], v[156:157] op_sel_hi:[1,0]
	v_pk_mul_f32 v[8:9], v[8:9], v[156:157] op_sel_hi:[1,0]
	v_pk_mul_f32 v[6:7], v[6:7], v[156:157] op_sel_hi:[1,0]
	v_pk_mul_f32 v[4:5], v[4:5], v[156:157] op_sel_hi:[1,0]

; #define LAS __attribute__((address_space(3)))
; #define MFMA32(a, b, c) __builtin_amdgcn_mfma_f32_32x32x16_bf16((a), (b), (c), 0, 0, 0)
;     __device__ __forceinline__ void begin(int k0) { set_base((float)(tq - k0)); }
;     __device__ __forceinline__ void begin(int k0) { set_base((float)(tq - k0)); }
;     __device__ __forceinline__ void begin(int k0) { set_base((float)(tq - k0)); }
;     __device__ __forceinline__ void begin(int k0) { set_base((float)(tq - 31 - 16 * k0) * (1.f / 16.f)); }
;     __device__ __forceinline__ void begin(int k0) { set_base((float)(iq - k0)); }
; template <int NDT, class F>
; __device__ __forceinline__ void coop_step(const bf16x8 (&qf)[4], const LAS unsigned char* buf, int fk, int fv, int vsub  , F& f, int st, int t0_mine, int hh, f32x16 (&o)[NDT], float& m, float& l) {
;     ...
;     if (k1 <= t0_mine) {
;         f32x16 sA, sB;
; #pragma unroll
;         for (int ks = 0; ks < 4; ++ks) { const bf16x8 kf = *(const LAS bf16x8*)(buf + 4096 + (fk ^ (ks << 5))); sA = MFMA32(kf, qf[ks], ks == 0 ? f.c1() : sA); }
;         if (NDT == 2) {
; #pragma unroll
;             for (int ks = 0; ks < 4; ++ks) { const bf16x8 kf = *(const LAS bf16x8*)(buf + (fk ^ (ks << 5))); sB = MFMA32(kf, qf[ks], ks == 0 ? f.c0() : sB); }
;             if (st > 0) f.fetch2(st - 1);
;             __builtin_amdgcn_sched_barrier(0); }
;         f.begin(k1); softmax_body<NDT>(sA, f, k1, hh, o, m, l, pf0, pf1, k1 == t0_mine ? 1 : 0);
; #pragma unroll
;         for (int dt = 0; dt < NDT; ++dt) { const bf16x8 vf0 = *(const LAS bf16x8*)(buf + 4096 + dt * 2048 + fv + vsub), vf1 = *(const LAS bf16x8*)(buf + 4096 + dt * 2048 + ((fv + vsub) ^ 32));
;             o[dt] = MFMA32(vf0, pf0, o[dt]); o[dt] = MFMA32(vf1, pf1, o[dt]); }
;         if (NDT != 2) {
; #pragma unroll
;             for (int ks = 0; ks < 4; ++ks) { const bf16x8 kf = *(const LAS bf16x8*)(buf + (fk ^ (ks << 5))); sB = MFMA32(kf, qf[ks], ks == 0 ? f.c0() : sB); }
;             if (st > 0) f.fetch2(st - 1); }
;         f.begin(k0); softmax_body<NDT>(sB, f, k0, hh, o, m, l, pf0, pf1, 0);
; #pragma unroll
;         for (int dt = 0; dt < NDT; ++dt) { const bf16x8 vf0 = *(const LAS bf16x8*)(buf + dt * 2048 + fv), vf1 = *(const LAS bf16x8*)(buf + dt * 2048 + (fv ^ 32));
;             o[dt] = MFMA32(vf0, pf0, o[dt]); o[dt] = MFMA32(vf1, pf1, o[dt]); }
.LBB0_635:
	v_max3_f32 v2, v82, s86, v83
	v_max3_f32 v2, v2, v84, v85
	v_max3_f32 v2, v2, v86, v87
	v_max3_f32 v2, v2, v88, v89
	v_max3_f32 v2, v2, v90, v91
	v_max3_f32 v2, v2, v92, v93
	v_max3_f32 v2, v2, v94, v95
	v_max3_f32 v2, v2, v96, v97
	v_fmamk_f32 v2, v2, 0x3e38aa3b, v241
	v_mov_b32_e32 v4, v2
	v_mov_b64_e32 v[144:145], v[32:33]
	s_nop 0
	v_permlane32_swap_b32_e32 v2, v4
	v_max_f32_e32 v4, v2, v4
	v_mov_b64_e32 v[128:129], v[48:49]
	v_cmp_gt_f32_e32 vcc, v4, v248
	v_mov_b64_e32 v[142:143], v[30:31]
	v_mov_b64_e32 v[140:141], v[28:29]
	v_mov_b64_e32 v[138:139], v[26:27]
	v_mov_b64_e32 v[136:137], v[24:25]
	v_mov_b64_e32 v[134:135], v[22:23]
	v_mov_b64_e32 v[132:133], v[20:21]
	v_mov_b64_e32 v[130:131], v[18:19]
	v_mov_b64_e32 v[126:127], v[46:47]
	v_mov_b64_e32 v[124:125], v[44:45]
	v_mov_b64_e32 v[122:123], v[42:43]
	v_mov_b64_e32 v[120:121], v[40:41]
	v_mov_b64_e32 v[118:119], v[38:39]
	v_mov_b64_e32 v[116:117], v[36:37]
	v_mov_b64_e32 v[114:115], v[34:35]
	v_mov_b32_e32 v2, v248
	v_mov_b32_e32 v6, v229
	s_cbranch_vccz .LBB0_637
	v_max_f32_e32 v2, v4, v4
	v_max_f32_e32 v4, v248, v248
	v_max_f32_e32 v2, v4, v2
	v_sub_f32_e32 v4, v248, v2
	v_exp_f32_e32 v4, v4
	s_nop 0
	v_mul_f32_e32 v6, v229, v4
	v_pk_mul_f32 v[128:129], v[48:49], v[4:5] op_sel_hi:[1,0]
	v_pk_mul_f32 v[126:127], v[46:47], v[4:5] op_sel_hi:[1,0]
	v_pk_mul_f32 v[124:125], v[44:45], v[4:5] op_sel_hi:[1,0]
	v_pk_mul_f32 v[122:123], v[42:43], v[4:5] op_sel_hi:[1,0]
	v_pk_mul_f32 v[120:121], v[40:41], v[4:5] op_sel_hi:[1,0]
	v_pk_mul_f32 v[118:119], v[38:39], v[4:5] op_sel_hi:[1,0]
	v_pk_mul_f32 v[116:117], v[36:37], v[4:5] op_sel_hi:[1,0]
	v_pk_mul_f32 v[114:115], v[34:35], v[4:5] op_sel_hi:[1,0]
	v_pk_mul_f32 v[144:145], v[32:33], v[4:5] op_sel_hi:[1,0]
	v_pk_mul_f32 v[142:143], v[30:31], v[4:5] op_sel_hi:[1,0]
	v_pk_mul_f32 v[140:141], v[28:29], v[4:5] op_sel_hi:[1,0]
	v_pk_mul_f32 v[138:139], v[26:27], v[4:5] op_sel_hi:[1,0]
	v_pk_mul_f32 v[136:137], v[24:25], v[4:5] op_sel_hi:[1,0]
	v_pk_mul_f32 v[134:135], v[22:23], v[4:5] op_sel_hi:[1,0]
	v_pk_mul_f32 v[132:133], v[20:21], v[4:5] op_sel_hi:[1,0]
	v_pk_mul_f32 v[130:131], v[18:19], v[4:5] op_sel_hi:[1,0]
.LBB0_637:
	v_max_f32_e32 v5, v2, v2
	v_max_f32_e32 v4, 0xefa18f08, v5
	v_sub_f32_e32 v4, v241, v4
	v_pk_fma_f32 v[8:9], v[82:83], s[34:35], v[4:5] op_sel_hi:[1,0,0]
	v_pk_fma_f32 v[12:13], v[84:85], s[34:35], v[4:5] op_sel_hi:[1,0,0]
	v_exp_f32_e32 v10, v8
	v_exp_f32_e32 v11, v9
	v_exp_f32_e32 v12, v12
	v_exp_f32_e32 v13, v13
	v_pk_fma_f32 v[14:15], v[86:87], s[34:35], v[4:5] op_sel_hi:[1,0,0]
	v_pk_fma_f32 v[16:17], v[88:89], s[34:35], v[4:5] op_sel_hi:[1,0,0]
	v_exp_f32_e32 v14, v14
	v_exp_f32_e32 v15, v15
	v_exp_f32_e32 v16, v16
	v_exp_f32_e32 v17, v17
	v_pk_fma_f32 v[82:83], v[90:91], s[34:35], v[4:5] op_sel_hi:[1,0,0]
	v_pk_add_f32 v[8:9], v[10:11], 0 op_sel_hi:[1,0]
	v_exp_f32_e32 v82, v82
	v_exp_f32_e32 v83, v83
	v_pk_fma_f32 v[84:85], v[92:93], s[34:35], v[4:5] op_sel_hi:[1,0,0]
	v_pk_add_f32 v[8:9], v[12:13], v[8:9]
	v_exp_f32_e32 v84, v84
	v_exp_f32_e32 v85, v85
	v_pk_fma_f32 v[86:87], v[94:95], s[34:35], v[4:5] op_sel_hi:[1,0,0]
	v_pk_add_f32 v[8:9], v[14:15], v[8:9]
	v_exp_f32_e32 v86, v86
	v_exp_f32_e32 v87, v87
	v_pk_fma_f32 v[88:89], v[96:97], s[34:35], v[4:5] op_sel_hi:[1,0,0]
	v_pk_add_f32 v[8:9], v[16:17], v[8:9]
	v_exp_f32_e32 v88, v88
	v_exp_f32_e32 v89, v89
	v_pk_add_f32 v[8:9], v[82:83], v[8:9]
	v_cvt_pk_bf16_f32 v10, v10, v11
	v_pk_add_f32 v[8:9], v[84:85], v[8:9]
	v_cvt_pk_bf16_f32 v11, v12, v13
	v_pk_add_f32 v[8:9], v[86:87], v[8:9]
	v_cvt_pk_bf16_f32 v12, v14, v15
	v_pk_add_f32 v[8:9], v[88:89], v[8:9]
	v_cvt_pk_bf16_f32 v14, v82, v83
	v_add_f32_e32 v7, v8, v9
	v_add_f32_e32 v8, v6, v7
	v_add_u32_e32 v7, 0, v243
	v_cvt_pk_bf16_f32 v15, v84, v85
	ds_read_b128 v[82:85], v7 offset:12288
	v_add_u32_e32 v6, 0, v247
	v_cvt_pk_bf16_f32 v13, v16, v17
	v_cvt_pk_bf16_f32 v16, v86, v87
	v_cvt_pk_bf16_f32 v17, v88, v89
	ds_read_b128 v[86:89], v6 offset:12288
	s_waitcnt lgkmcnt(1)
	v_mfma_f32_32x32x16_bf16 v[114:129], v[82:85], v[10:13], v[114:129]
	v_max3_f32 v9, v146, s86, v147
	v_max3_f32 v9, v9, v148, v149
	v_max3_f32 v9, v9, v150, v151
	v_max3_f32 v9, v9, v152, v153
	v_max3_f32 v9, v9, v154, v155
	v_max3_f32 v9, v9, v156, v157
	v_max3_f32 v9, v9, v158, v159
	s_waitcnt lgkmcnt(0)
	v_mfma_f32_32x32x16_bf16 v[114:129], v[86:89], v[14:17], v[114:129]
	ds_read_b128 v[82:85], v7 offset:14336
	ds_read_b128 v[86:89], v6 offset:14336
	v_max3_f32 v9, v9, v160, v161
	v_fmamk_f32 v9, v9, 0x3e38aa3b, v241
	s_waitcnt lgkmcnt(1)
	v_mfma_f32_32x32x16_bf16 v[130:145], v[82:85], v[10:13], v[130:145]
	v_mov_b32_e32 v10, v9
	s_nop 1
	v_permlane32_swap_b32_e32 v9, v10
	s_waitcnt lgkmcnt(0)
	v_mfma_f32_32x32x16_bf16 v[130:145], v[86:89], v[14:17], v[130:145]
	v_max_f32_e32 v9, v9, v10
	v_cmp_gt_f32_e32 vcc, v9, v2
	s_cbranch_vccz .LBB0_639
	v_max_f32_e32 v4, v9, v9
	v_max_f32_e32 v5, v5, v4
	v_sub_f32_e32 v2, v2, v5
	v_exp_f32_e32 v2, v2
	s_nop 0
	v_mul_f32_e32 v8, v2, v8
	v_pk_mul_f32 v[128:129], v[128:129], v[2:3] op_sel_hi:[1,0]
	v_pk_mul_f32 v[126:127], v[126:127], v[2:3] op_sel_hi:[1,0]
	v_pk_mul_f32 v[124:125], v[124:125], v[2:3] op_sel_hi:[1,0]
	v_pk_mul_f32 v[122:123], v[122:123], v[2:3] op_sel_hi:[1,0]
	v_pk_mul_f32 v[120:121], v[120:121], v[2:3] op_sel_hi:[1,0]
	v_pk_mul_f32 v[118:119], v[118:119], v[2:3] op_sel_hi:[1,0]
	v_pk_mul_f32 v[116:117], v[116:117], v[2:3] op_sel_hi:[1,0]
	v_pk_mul_f32 v[114:115], v[114:115], v[2:3] op_sel_hi:[1,0]
	v_pk_mul_f32 v[144:145], v[144:145], v[2:3] op_sel_hi:[1,0]
	v_pk_mul_f32 v[142:143], v[142:143], v[2:3] op_sel_hi:[1,0]
	v_pk_mul_f32 v[140:141], v[140:141], v[2:3] op_sel_hi:[1,0]
	v_pk_mul_f32 v[138:139], v[138:139], v[2:3] op_sel_hi:[1,0]
	v_pk_mul_f32 v[136:137], v[136:137], v[2:3] op_sel_hi:[1,0]
	v_pk_mul_f32 v[134:135], v[134:135], v[2:3] op_sel_hi:[1,0]
	v_pk_mul_f32 v[132:133], v[132:133], v[2:3] op_sel_hi:[1,0]
	v_pk_mul_f32 v[130:131], v[130:131], v[2:3] op_sel_hi:[1,0]
	v_max_f32_e32 v2, 0xefa18f08, v5
	v_sub_f32_e32 v4, v241, v2
	v_mov_b32_e32 v2, v5

; #define GAS __attribute__((address_space(1)))
; #define LAS __attribute__((address_space(3)))
; #define MFMA32(a, b, c) __builtin_amdgcn_mfma_f32_32x32x16_bf16((a), (b), (c), 0, 0, 0)
;     __device__ __forceinline__ void begin(int k0) { set_base((float)(tq - k0)); }
;     __device__ __forceinline__ void begin(int k0) { set_base((float)(tq - k0)); }
;     __device__ __forceinline__ void begin(int k0) { set_base((float)(tq - k0)); }
;     __device__ __forceinline__ void begin(int k0) { set_base((float)(tq - 31 - 16 * k0) * (1.f / 16.f)); }
;     __device__ __forceinline__ void begin(int k0) { set_base((float)(iq - k0)); }
;     __device__ __forceinline__ void fetch2(int st) {
; #pragma unroll
;         for (int g = 0; g < 4; ++g) { const f32x4 a = *(const GAS f32x4*)(cum2 + 64 * st + 32 + 8 * g + 4 * hh), b = *(const GAS f32x4*)(cum2 + 64 * st + 8 * g + 4 * hh);
;             cvA[4 * g] = a.x; cvA[4 * g + 1] = a.y; cvA[4 * g + 2] = a.z; cvA[4 * g + 3] = a.w; cvB[4 * g] = b.x; cvB[4 * g + 1] = b.y; cvB[4 * g + 2] = b.z; cvB[4 * g + 3] = b.w; } }
; template <int NDT, class F>
; __device__ __forceinline__ void coop_step(const bf16x8 (&qf)[4], const LAS unsigned char* buf, int fk, int fv, int vsub  , F& f, int st, int t0_mine, int hh, f32x16 (&o)[NDT], float& m, float& l) {
;     ...
;     } else {
;         f32x16 sB;
; #pragma unroll
;         for (int ks = 0; ks < 4; ++ks) { const bf16x8 kf = *(const LAS bf16x8*)(buf + (fk ^ (ks << 5))); sB = MFMA32(kf, qf[ks], ks == 0 ? f.c0() : sB); }
;         if (st > 0) f.fetch2(st - 1);
;         f.begin(k0); softmax_body<NDT>(sB, f, k0, hh, o, m, l, pf0, pf1, 1);
.LBB0_640:
	s_and_b64 vcc, exec, s[16:17]
	s_cbranch_vccz .LBB0_644
	v_add_u32_e32 v2, 0, v242
	ds_read_b128 v[4:7], v2
	v_add_u32_e32 v2, 0, v244
	s_add_i32 s4, s20, 0x80
	s_ashr_i32 s5, s4, 31
	s_waitcnt lgkmcnt(0)
	v_mfma_f32_32x32x16_bf16 v[50:65], v[4:7], v[162:165], v[50:65]
	ds_read_b128 v[4:7], v2
	v_add_u32_e32 v2, 0, v245
	s_waitcnt lgkmcnt(0)
	v_mfma_f32_32x32x16_bf16 v[50:65], v[4:7], v[166:169], v[50:65]
	ds_read_b128 v[4:7], v2
	v_add_u32_e32 v2, 0, v246
	s_waitcnt lgkmcnt(0)
	v_mfma_f32_32x32x16_bf16 v[50:65], v[4:7], v[170:173], v[50:65]
	ds_read_b128 v[4:7], v2
	v_add_u32_e32 v2, s20, v1
	v_add_u32_e32 v8, 0xc8, v2
	v_add_u32_e32 v9, 0xc9, v2
	v_add_u32_e32 v10, 0xca, v2
	v_add_u32_e32 v11, 0xd9, v2
	v_add_u32_e32 v12, 0xda, v2
	s_waitcnt lgkmcnt(0)
	v_mfma_f32_32x32x16_bf16 v[50:65], v[4:7], v[174:177], v[50:65]
	v_lshl_add_u64 v[4:5], s[4:5], 2, v[226:227]
	global_load_dwordx4 v[98:101], v[4:5], off offset:128
	global_load_dwordx4 v[66:69], v[4:5], off
	global_load_dwordx4 v[102:105], v[4:5], off offset:160
	global_load_dwordx4 v[70:73], v[4:5], off offset:32
	global_load_dwordx4 v[106:109], v[4:5], off offset:192
	global_load_dwordx4 v[74:77], v[4:5], off offset:64
	global_load_dwordx4 v[110:113], v[4:5], off offset:224
	global_load_dwordx4 v[78:81], v[4:5], off offset:96
	v_add_u32_e32 v5, 0xc0, v2
	v_cmp_le_i32_e32 vcc, v5, v220
	v_add_u32_e32 v6, 0xc2, v2
	v_add_u32_e32 v7, 0xc3, v2
	v_cndmask_b32_e32 v4, v235, v50, vcc
	v_cmp_lt_i32_e32 vcc, v5, v220
	s_nop 1
	v_cndmask_b32_e32 v5, v235, v51, vcc
	v_cmp_le_i32_e32 vcc, v6, v220
	s_nop 1
	v_cndmask_b32_e32 v6, v235, v52, vcc
	v_cmp_le_i32_e32 vcc, v7, v220
	s_nop 1
	v_cndmask_b32_e32 v7, v235, v53, vcc
	v_cmp_le_i32_e32 vcc, v8, v220
	s_nop 1
	v_cndmask_b32_e32 v8, v235, v54, vcc
	v_cmp_le_i32_e32 vcc, v9, v220
	s_nop 1
	v_cndmask_b32_e32 v9, v235, v55, vcc
	v_cmp_le_i32_e32 vcc, v10, v220
	v_add_u32_e32 v10, 0xcb, v2
	s_nop 0
	v_cndmask_b32_e32 v50, v235, v56, vcc
	v_cmp_le_i32_e32 vcc, v10, v220
	v_add_u32_e32 v10, 0xd0, v2
	s_nop 0
	v_cndmask_b32_e32 v51, v235, v57, vcc
	v_cmp_le_i32_e32 vcc, v10, v220
	v_add_u32_e32 v10, 0xd1, v2
	s_nop 0
	v_cndmask_b32_e32 v16, v235, v58, vcc
	v_cmp_le_i32_e32 vcc, v10, v220
	v_add_u32_e32 v10, 0xd2, v2
	s_nop 0
	v_cndmask_b32_e32 v17, v235, v59, vcc
	v_cmp_le_i32_e32 vcc, v10, v220
	v_add_u32_e32 v10, 0xd3, v2
	s_nop 0
	v_cndmask_b32_e32 v14, v235, v60, vcc
	v_cmp_le_i32_e32 vcc, v10, v220
	v_add_u32_e32 v10, 0xd8, v2
	v_add_u32_e32 v2, 0xdb, v2
	v_cndmask_b32_e32 v15, v235, v61, vcc
	v_cmp_le_i32_e32 vcc, v10, v220
	s_nop 1
	v_cndmask_b32_e32 v10, v235, v62, vcc
	v_cmp_le_i32_e32 vcc, v11, v220
	s_nop 1
	v_cndmask_b32_e32 v11, v235, v63, vcc
	v_cmp_le_i32_e32 vcc, v12, v220
	s_nop 1
	v_cndmask_b32_e32 v12, v235, v64, vcc
	v_cmp_le_i32_e32 vcc, v2, v220
	v_max3_f32 v2, v4, s86, v5
	v_max3_f32 v2, v2, v6, v7
	v_max3_f32 v2, v2, v8, v9
	v_max3_f32 v2, v2, v50, v51
	v_max3_f32 v2, v2, v16, v17
	v_max3_f32 v2, v2, v14, v15
	v_cndmask_b32_e32 v13, v235, v65, vcc
	v_max3_f32 v2, v2, v10, v11
	v_max3_f32 v2, v2, v12, v13
	v_fmamk_f32 v2, v2, 0x3e38aa3b, v241
	v_mov_b32_e32 v52, v2
	s_nop 1
	v_permlane32_swap_b32_e32 v2, v52
	v_max_f32_e32 v2, v2, v52
	v_cmp_gt_f32_e32 vcc, v2, v248
	s_cbranch_vccz .LBB0_643
	v_max_f32_e32 v52, v248, v248
	v_max_f32_e32 v52, v52, v2
	v_sub_f32_e32 v2, v248, v52
	v_exp_f32_e32 v2, v2
	v_mov_b32_e32 v248, v52
	v_mul_f32_e32 v229, v229, v2
	v_pk_mul_f32 v[48:49], v[48:49], v[2:3] op_sel_hi:[1,0]
	v_pk_mul_f32 v[46:47], v[46:47], v[2:3] op_sel_hi:[1,0]
	v_pk_mul_f32 v[44:45], v[44:45], v[2:3] op_sel_hi:[1,0]
	v_pk_mul_f32 v[42:43], v[42:43], v[2:3] op_sel_hi:[1,0]
	v_pk_mul_f32 v[40:41], v[40:41], v[2:3] op_sel_hi:[1,0]
	v_pk_mul_f32 v[38:39], v[38:39], v[2:3] op_sel_hi:[1,0]
	v_pk_mul_f32 v[36:37], v[36:37], v[2:3] op_sel_hi:[1,0]
	v_pk_mul_f32 v[34:35], v[34:35], v[2:3] op_sel_hi:[1,0]
	v_pk_mul_f32 v[32:33], v[32:33], v[2:3] op_sel_hi:[1,0]
	v_pk_mul_f32 v[30:31], v[30:31], v[2:3] op_sel_hi:[1,0]
	v_pk_mul_f32 v[28:29], v[28:29], v[2:3] op_sel_hi:[1,0]
	v_pk_mul_f32 v[26:27], v[26:27], v[2:3] op_sel_hi:[1,0]
	v_pk_mul_f32 v[24:25], v[24:25], v[2:3] op_sel_hi:[1,0]
	v_pk_mul_f32 v[22:23], v[22:23], v[2:3] op_sel_hi:[1,0]
	v_pk_mul_f32 v[20:21], v[20:21], v[2:3] op_sel_hi:[1,0]
	v_pk_mul_f32 v[18:19], v[18:19], v[2:3] op_sel_hi:[1,0]

; #define LAS __attribute__((address_space(3)))
; #define MFMA32(a, b, c) __builtin_amdgcn_mfma_f32_32x32x16_bf16((a), (b), (c), 0, 0, 0)
;     __device__ __forceinline__ void begin(int k0) { set_base((float)(tq - k0)); }
;     __device__ __forceinline__ void begin(int k0) { set_base((float)(tq - k0)); }
;     __device__ __forceinline__ void begin(int k0) { set_base((float)(tq - k0)); }
;     __device__ __forceinline__ void begin(int k0) { set_base((float)(tq - 31 - 16 * k0) * (1.f / 16.f)); }
;     __device__ __forceinline__ void begin(int k0) { set_base((float)(iq - k0)); }
; template <int NDT, class F>
; __device__ __forceinline__ void coop_step(const bf16x8 (&qf)[4], const LAS unsigned char* buf, int fk, int fv, int vsub  , F& f, int st, int t0_mine, int hh, f32x16 (&o)[NDT], float& m, float& l) {
;     ...
;     if (k1 <= t0_mine) {
;         f32x16 sA, sB;
; #pragma unroll
;         for (int ks = 0; ks < 4; ++ks) { const bf16x8 kf = *(const LAS bf16x8*)(buf + 4096 + (fk ^ (ks << 5))); sA = MFMA32(kf, qf[ks], ks == 0 ? f.c1() : sA); }
;         if (NDT == 2) {
; #pragma unroll
;             for (int ks = 0; ks < 4; ++ks) { const bf16x8 kf = *(const LAS bf16x8*)(buf + (fk ^ (ks << 5))); sB = MFMA32(kf, qf[ks], ks == 0 ? f.c0() : sB); }
;             if (st > 0) f.fetch2(st - 1);
;             __builtin_amdgcn_sched_barrier(0); }
;         f.begin(k1); softmax_body<NDT>(sA, f, k1, hh, o, m, l, pf0, pf1, k1 == t0_mine ? 1 : 0);
; #pragma unroll
;         for (int dt = 0; dt < NDT; ++dt) { const bf16x8 vf0 = *(const LAS bf16x8*)(buf + 4096 + dt * 2048 + fv + vsub), vf1 = *(const LAS bf16x8*)(buf + 4096 + dt * 2048 + ((fv + vsub) ^ 32));
;             o[dt] = MFMA32(vf0, pf0, o[dt]); o[dt] = MFMA32(vf1, pf1, o[dt]); }
;         if (NDT != 2) {
; #pragma unroll
;             for (int ks = 0; ks < 4; ++ks) { const bf16x8 kf = *(const LAS bf16x8*)(buf + (fk ^ (ks << 5))); sB = MFMA32(kf, qf[ks], ks == 0 ? f.c0() : sB); }
;             if (st > 0) f.fetch2(st - 1); }
;         f.begin(k0); softmax_body<NDT>(sB, f, k0, hh, o, m, l, pf0, pf1, 0);
; #pragma unroll
;         for (int dt = 0; dt < NDT; ++dt) { const bf16x8 vf0 = *(const LAS bf16x8*)(buf + dt * 2048 + fv), vf1 = *(const LAS bf16x8*)(buf + dt * 2048 + (fv ^ 32));
;             o[dt] = MFMA32(vf0, pf0, o[dt]); o[dt] = MFMA32(vf1, pf1, o[dt]); }
.LBB0_654:
	v_max3_f32 v16, v98, s86, v99
	v_max3_f32 v16, v16, v100, v101
	v_max3_f32 v16, v16, v102, v103
	v_max3_f32 v16, v16, v104, v105
	v_max3_f32 v16, v16, v106, v107
	v_max3_f32 v16, v16, v108, v109
	v_max3_f32 v16, v16, v110, v111
	v_max3_f32 v16, v16, v112, v113
	v_fmamk_f32 v16, v16, 0x3e38aa3b, v241
	v_mov_b32_e32 v17, v16
	v_mov_b64_e32 v[144:145], v[32:33]
	s_nop 0
	v_permlane32_swap_b32_e32 v16, v17
	v_max_f32_e32 v16, v16, v17
	v_mov_b64_e32 v[128:129], v[48:49]
	v_cmp_gt_f32_e32 vcc, v16, v248
	v_mov_b64_e32 v[142:143], v[30:31]
	v_mov_b64_e32 v[140:141], v[28:29]
	v_mov_b64_e32 v[138:139], v[26:27]
	v_mov_b64_e32 v[136:137], v[24:25]
	v_mov_b64_e32 v[134:135], v[22:23]
	v_mov_b64_e32 v[132:133], v[20:21]
	v_mov_b64_e32 v[130:131], v[18:19]
	v_mov_b64_e32 v[126:127], v[46:47]
	v_mov_b64_e32 v[124:125], v[44:45]
	v_mov_b64_e32 v[122:123], v[42:43]
	v_mov_b64_e32 v[120:121], v[40:41]
	v_mov_b64_e32 v[118:119], v[38:39]
	v_mov_b64_e32 v[116:117], v[36:37]
	v_mov_b64_e32 v[114:115], v[34:35]
	v_mov_b32_e32 v253, v248
	v_mov_b32_e32 v249, v229
	s_cbranch_vccz .LBB0_656
	v_max_f32_e32 v17, v248, v248
	v_max_f32_e32 v253, v17, v16
	v_sub_f32_e32 v16, v248, v253
	v_exp_f32_e32 v16, v16
	s_nop 0
	v_mul_f32_e32 v249, v229, v16
	v_pk_mul_f32 v[128:129], v[48:49], v[16:17] op_sel_hi:[1,0]
	v_pk_mul_f32 v[126:127], v[46:47], v[16:17] op_sel_hi:[1,0]
	v_pk_mul_f32 v[124:125], v[44:45], v[16:17] op_sel_hi:[1,0]
	v_pk_mul_f32 v[122:123], v[42:43], v[16:17] op_sel_hi:[1,0]
	v_pk_mul_f32 v[120:121], v[40:41], v[16:17] op_sel_hi:[1,0]
	v_pk_mul_f32 v[118:119], v[38:39], v[16:17] op_sel_hi:[1,0]
	v_pk_mul_f32 v[116:117], v[36:37], v[16:17] op_sel_hi:[1,0]
	v_pk_mul_f32 v[114:115], v[34:35], v[16:17] op_sel_hi:[1,0]
	v_pk_mul_f32 v[144:145], v[32:33], v[16:17] op_sel_hi:[1,0]
	v_pk_mul_f32 v[142:143], v[30:31], v[16:17] op_sel_hi:[1,0]
	v_pk_mul_f32 v[140:141], v[28:29], v[16:17] op_sel_hi:[1,0]
	v_pk_mul_f32 v[138:139], v[26:27], v[16:17] op_sel_hi:[1,0]
	v_pk_mul_f32 v[136:137], v[24:25], v[16:17] op_sel_hi:[1,0]
	v_pk_mul_f32 v[134:135], v[22:23], v[16:17] op_sel_hi:[1,0]
	v_pk_mul_f32 v[132:133], v[20:21], v[16:17] op_sel_hi:[1,0]
	v_pk_mul_f32 v[130:131], v[18:19], v[16:17] op_sel_hi:[1,0]
.LBB0_656:
	v_max_f32_e32 v17, v253, v253
	v_max_f32_e32 v16, 0xefa18f08, v17
	v_sub_f32_e32 v16, v241, v16
	v_pk_fma_f32 v[98:99], v[98:99], s[34:35], v[16:17] op_sel_hi:[1,0,0]
	v_pk_fma_f32 v[100:101], v[100:101], s[34:35], v[16:17] op_sel_hi:[1,0,0]
	v_exp_f32_e32 v98, v98
	v_exp_f32_e32 v99, v99
	v_exp_f32_e32 v216, v100
	v_exp_f32_e32 v217, v101
	v_pk_fma_f32 v[102:103], v[102:103], s[34:35], v[16:17] op_sel_hi:[1,0,0]
	v_pk_add_f32 v[214:215], v[98:99], 0 op_sel_hi:[1,0]
	s_nop 0
	v_pk_add_f32 v[100:101], v[216:217], v[214:215]
	v_exp_f32_e32 v214, v102
	v_exp_f32_e32 v215, v103
	v_pk_fma_f32 v[102:103], v[104:105], s[34:35], v[16:17] op_sel_hi:[1,0,0]
	v_pk_add_f32 v[100:101], v[214:215], v[100:101]
	v_exp_f32_e32 v232, v102
	v_exp_f32_e32 v233, v103
	v_pk_fma_f32 v[102:103], v[106:107], s[34:35], v[16:17] op_sel_hi:[1,0,0]
	v_cvt_pk_bf16_f32 v104, v214, v215
	v_exp_f32_e32 v106, v102
	v_exp_f32_e32 v107, v103
	v_pk_fma_f32 v[102:103], v[108:109], s[34:35], v[16:17] op_sel_hi:[1,0,0]
	v_pk_add_f32 v[100:101], v[232:233], v[100:101]
	v_exp_f32_e32 v108, v102
	v_exp_f32_e32 v109, v103
	v_pk_fma_f32 v[102:103], v[110:111], s[34:35], v[16:17] op_sel_hi:[1,0,0]
	v_pk_add_f32 v[100:101], v[106:107], v[100:101]
	v_exp_f32_e32 v110, v102
	v_exp_f32_e32 v111, v103
	v_pk_fma_f32 v[102:103], v[112:113], s[34:35], v[16:17] op_sel_hi:[1,0,0]
	v_pk_add_f32 v[100:101], v[108:109], v[100:101]
	v_exp_f32_e32 v112, v102
	v_exp_f32_e32 v113, v103
	v_pk_add_f32 v[100:101], v[110:111], v[100:101]
	v_cvt_pk_bf16_f32 v102, v98, v99
	v_add_u32_e32 v99, 0, v243
	v_pk_add_f32 v[100:101], v[112:113], v[100:101]
	v_cvt_pk_bf16_f32 v106, v106, v107
	v_cvt_pk_bf16_f32 v107, v108, v109
	v_cvt_pk_bf16_f32 v108, v110, v111
	v_cvt_pk_bf16_f32 v109, v112, v113
	ds_read_b128 v[110:113], v99 offset:28672
	v_add_u32_e32 v98, 0, v247
	v_cvt_pk_bf16_f32 v103, v216, v217
	v_cvt_pk_bf16_f32 v105, v232, v233
	ds_read_b128 v[214:217], v98 offset:28672
	v_add_f32_e32 v100, v100, v101
	s_waitcnt lgkmcnt(1)
	v_mfma_f32_32x32x16_bf16 v[114:129], v[110:113], v[102:105], v[114:129]
	v_max3_f32 v101, v146, s86, v147
	v_max3_f32 v101, v101, v148, v149
	v_max3_f32 v101, v101, v150, v151
	v_max3_f32 v101, v101, v152, v153
	v_max3_f32 v101, v101, v154, v155
	v_max3_f32 v101, v101, v156, v157
	v_max3_f32 v101, v101, v158, v159
	s_waitcnt lgkmcnt(0)
	v_mfma_f32_32x32x16_bf16 v[114:129], v[214:217], v[106:109], v[114:129]
	ds_read_b128 v[110:113], v99 offset:30720
	ds_read_b128 v[214:217], v98 offset:30720
	v_max3_f32 v101, v101, v160, v161
	v_fmamk_f32 v101, v101, 0x3e38aa3b, v241
	v_add_f32_e32 v100, v249, v100
	s_waitcnt lgkmcnt(1)
	v_mfma_f32_32x32x16_bf16 v[130:145], v[110:113], v[102:105], v[130:145]
	v_mov_b32_e32 v102, v101
	s_nop 1
	v_permlane32_swap_b32_e32 v101, v102
	s_waitcnt lgkmcnt(0)
	v_mfma_f32_32x32x16_bf16 v[130:145], v[214:217], v[106:109], v[130:145]
	v_max_f32_e32 v101, v101, v102
	v_cmp_gt_f32_e32 vcc, v101, v253
	s_cbranch_vccz .LBB0_658
	v_max_f32_e32 v16, v101, v101
	v_max_f32_e32 v17, v17, v16
	v_sub_f32_e32 v16, v253, v17
	v_exp_f32_e32 v16, v16
	v_mov_b32_e32 v253, v17
	v_mul_f32_e32 v100, v16, v100
	v_pk_mul_f32 v[128:129], v[128:129], v[16:17] op_sel_hi:[1,0]
	v_pk_mul_f32 v[126:127], v[126:127], v[16:17] op_sel_hi:[1,0]
	v_pk_mul_f32 v[124:125], v[124:125], v[16:17] op_sel_hi:[1,0]
	v_pk_mul_f32 v[122:123], v[122:123], v[16:17] op_sel_hi:[1,0]
	v_pk_mul_f32 v[120:121], v[120:121], v[16:17] op_sel_hi:[1,0]
	v_pk_mul_f32 v[118:119], v[118:119], v[16:17] op_sel_hi:[1,0]
	v_pk_mul_f32 v[116:117], v[116:117], v[16:17] op_sel_hi:[1,0]
	v_pk_mul_f32 v[114:115], v[114:115], v[16:17] op_sel_hi:[1,0]
	v_pk_mul_f32 v[144:145], v[144:145], v[16:17] op_sel_hi:[1,0]
	v_pk_mul_f32 v[142:143], v[142:143], v[16:17] op_sel_hi:[1,0]
	v_pk_mul_f32 v[140:141], v[140:141], v[16:17] op_sel_hi:[1,0]
	v_pk_mul_f32 v[138:139], v[138:139], v[16:17] op_sel_hi:[1,0]
	v_pk_mul_f32 v[136:137], v[136:137], v[16:17] op_sel_hi:[1,0]
	v_pk_mul_f32 v[134:135], v[134:135], v[16:17] op_sel_hi:[1,0]
	v_pk_mul_f32 v[132:133], v[132:133], v[16:17] op_sel_hi:[1,0]
	v_pk_mul_f32 v[130:131], v[130:131], v[16:17] op_sel_hi:[1,0]
	v_max_f32_e32 v16, 0xefa18f08, v17
	v_sub_f32_e32 v16, v241, v16

; __device__ __forceinline__ float half_max(float v) { unsigned a, b; half_swap(__builtin_bit_cast(unsigned, v), a, b); return fmaxf(__builtin_bit_cast(float, a), __builtin_bit_cast(float, b)); }
; template <int NDT, class F>
; __device__ __forceinline__ void softmax_body(f32x16& s, const F& f, int k0, int hh, f32x16 (&o)[NDT], float& m, float& l, bf16x8& pf0, bf16x8& pf1, const int MASK) {
;     float mx = NEG_BIG;
;     if (MASK == 1) {
; #pragma unroll
;         for (int r = 0; r < 16; ++r) s[r] = f.valid(k0 + CR(r) + 4 * hh) ? s[r] : NEG_BIG; }
; #pragma unroll
;     for (int r = 0; r < 16; ++r) mx = fmaxf(mx, s[r]);
;     mx = fmaf(mx, QK_SCL, f.tadd);
;     const bool on = MASK != 2 || f.lane_on();
;     mx = on ? mx : NEG_BIG;
;     mx = half_max(mx);
;     if (__ballot(mx > m) != 0ull) { const float mn = fmaxf(m, mx), alpha = __builtin_amdgcn_exp2f(m - mn); m = mn; l *= alpha;
; #pragma unroll
;         for (int dt = 0; dt < NDT; ++dt) o[dt] = o[dt] * alpha; }
.LBB0_662:
	v_add_u32_e32 v2, s20, v1
	v_add_u32_e32 v4, 0x80, v2
	v_cmp_le_i32_e32 vcc, v4, v220
	v_add_u32_e32 v5, 0x99, v2
	v_add_u32_e32 v6, 0x9a, v2
	s_nop 5
	v_cndmask_b32_e32 v66, v235, v66, vcc
	v_cmp_lt_i32_e32 vcc, v4, v220
	v_add_u32_e32 v4, 0x82, v2
	s_nop 0
	v_cndmask_b32_e32 v67, v235, v67, vcc
	v_cmp_le_i32_e32 vcc, v4, v220
	v_add_u32_e32 v4, 0x83, v2
	s_nop 0
	v_cndmask_b32_e32 v16, v235, v68, vcc
	v_cmp_le_i32_e32 vcc, v4, v220
	v_add_u32_e32 v4, 0x88, v2
	s_nop 0
	v_cndmask_b32_e32 v17, v235, v69, vcc
	v_cmp_le_i32_e32 vcc, v4, v220
	v_add_u32_e32 v4, 0x89, v2
	s_nop 0
	v_cndmask_b32_e32 v14, v235, v70, vcc
	v_cmp_le_i32_e32 vcc, v4, v220
	v_add_u32_e32 v4, 0x8a, v2
	s_nop 0
	v_cndmask_b32_e32 v15, v235, v71, vcc
	v_cmp_le_i32_e32 vcc, v4, v220
	v_add_u32_e32 v4, 0x8b, v2
	s_nop 0
	v_cndmask_b32_e32 v12, v235, v72, vcc
	v_cmp_le_i32_e32 vcc, v4, v220
	v_add_u32_e32 v4, 0x90, v2
	s_nop 0
	v_cndmask_b32_e32 v13, v235, v73, vcc
	v_cmp_le_i32_e32 vcc, v4, v220
	v_add_u32_e32 v4, 0x91, v2
	s_nop 0
	v_cndmask_b32_e32 v10, v235, v74, vcc
	v_cmp_le_i32_e32 vcc, v4, v220
	v_add_u32_e32 v4, 0x92, v2
	s_nop 0
	v_cndmask_b32_e32 v11, v235, v75, vcc
	v_cmp_le_i32_e32 vcc, v4, v220
	v_add_u32_e32 v4, 0x93, v2
	s_nop 0
	v_cndmask_b32_e32 v8, v235, v76, vcc
	v_cmp_le_i32_e32 vcc, v4, v220
	v_add_u32_e32 v4, 0x98, v2
	v_add_u32_e32 v2, 0x9b, v2
	v_cndmask_b32_e32 v9, v235, v77, vcc
	v_cmp_le_i32_e32 vcc, v4, v220
	s_nop 1
	v_cndmask_b32_e32 v4, v235, v78, vcc
	v_cmp_le_i32_e32 vcc, v5, v220
	s_nop 1
	v_cndmask_b32_e32 v5, v235, v79, vcc
	v_cmp_le_i32_e32 vcc, v6, v220
	s_nop 1
	v_cndmask_b32_e32 v6, v235, v80, vcc
	v_cmp_le_i32_e32 vcc, v2, v220
	v_max3_f32 v2, v66, s86, v67
	v_max3_f32 v2, v2, v16, v17
	v_max3_f32 v2, v2, v14, v15
	v_max3_f32 v2, v2, v12, v13
	v_max3_f32 v2, v2, v10, v11
	v_max3_f32 v2, v2, v8, v9
	v_cndmask_b32_e32 v7, v235, v81, vcc
	v_max3_f32 v2, v2, v4, v5
	v_max3_f32 v2, v2, v6, v7
	v_fmamk_f32 v2, v2, 0x3e38aa3b, v241
	v_mov_b32_e32 v68, v2
	s_nop 1
	v_permlane32_swap_b32_e32 v2, v68
	v_max_f32_e32 v2, v2, v68
	v_cmp_gt_f32_e32 vcc, v2, v248
	s_cbranch_vccz .LBB0_664
	v_max_f32_e32 v68, v248, v248
	v_max_f32_e32 v68, v68, v2
	v_sub_f32_e32 v2, v248, v68
	v_exp_f32_e32 v2, v2
	v_mov_b32_e32 v248, v68
	v_mul_f32_e32 v229, v229, v2
	v_pk_mul_f32 v[48:49], v[48:49], v[2:3] op_sel_hi:[1,0]
	v_pk_mul_f32 v[46:47], v[46:47], v[2:3] op_sel_hi:[1,0]
	v_pk_mul_f32 v[44:45], v[44:45], v[2:3] op_sel_hi:[1,0]
	v_pk_mul_f32 v[42:43], v[42:43], v[2:3] op_sel_hi:[1,0]
	v_pk_mul_f32 v[40:41], v[40:41], v[2:3] op_sel_hi:[1,0]
	v_pk_mul_f32 v[38:39], v[38:39], v[2:3] op_sel_hi:[1,0]
	v_pk_mul_f32 v[36:37], v[36:37], v[2:3] op_sel_hi:[1,0]
	v_pk_mul_f32 v[34:35], v[34:35], v[2:3] op_sel_hi:[1,0]
	v_pk_mul_f32 v[32:33], v[32:33], v[2:3] op_sel_hi:[1,0]
	v_pk_mul_f32 v[30:31], v[30:31], v[2:3] op_sel_hi:[1,0]
	v_pk_mul_f32 v[28:29], v[28:29], v[2:3] op_sel_hi:[1,0]
	v_pk_mul_f32 v[26:27], v[26:27], v[2:3] op_sel_hi:[1,0]
	v_pk_mul_f32 v[24:25], v[24:25], v[2:3] op_sel_hi:[1,0]
	v_pk_mul_f32 v[22:23], v[22:23], v[2:3] op_sel_hi:[1,0]
	v_pk_mul_f32 v[20:21], v[20:21], v[2:3] op_sel_hi:[1,0]
	v_pk_mul_f32 v[18:19], v[18:19], v[2:3] op_sel_hi:[1,0]

; __device__ __forceinline__ float half_max(float v) { unsigned a, b; half_swap(__builtin_bit_cast(unsigned, v), a, b); return fmaxf(__builtin_bit_cast(float, a), __builtin_bit_cast(float, b)); }
; template <int NDT, class F>
; __device__ __forceinline__ void softmax_body(f32x16& s, const F& f, int k0, int hh, f32x16 (&o)[NDT], float& m, float& l, bf16x8& pf0, bf16x8& pf1, const int MASK) {
;     float mx = NEG_BIG;
;     if (MASK == 1) {
; #pragma unroll
;         for (int r = 0; r < 16; ++r) s[r] = f.valid(k0 + CR(r) + 4 * hh) ? s[r] : NEG_BIG; }
; #pragma unroll
;     for (int r = 0; r < 16; ++r) mx = fmaxf(mx, s[r]);
;     mx = fmaf(mx, QK_SCL, f.tadd);
;     const bool on = MASK != 2 || f.lane_on();
;     mx = on ? mx : NEG_BIG;
;     mx = half_max(mx);
;     if (__ballot(mx > m) != 0ull) { const float mn = fmaxf(m, mx), alpha = __builtin_amdgcn_exp2f(m - mn); m = mn; l *= alpha;
; #pragma unroll
;         for (int dt = 0; dt < NDT; ++dt) o[dt] = o[dt] * alpha; }
.LBB0_725:
	s_nop 10
	v_max3_f32 v80, v52, s86, v53
	v_max3_f32 v80, v80, v54, v55
	v_subrev_u32_e32 v79, s79, v116
	v_max3_f32 v80, v80, v56, v57
	v_cvt_f32_i32_e32 v79, v79
	v_max3_f32 v80, v80, v58, v59
	v_max3_f32 v80, v80, v60, v61
	s_cmp_eq_u64 s[38:39], -1
	v_max3_f32 v80, v80, v62, v63
	s_cselect_b64 s[38:39], -1, 0
	v_max3_f32 v80, v80, v64, v65
	v_mul_f32_e64 v79, -v1, v79
	v_max3_f32 v80, v80, v66, v67
	s_or_b64 s[20:21], s[20:21], s[38:39]
	v_fmamk_f32 v80, v80, 0x3e38aa3b, v79
	s_or_b64 s[38:39], s[20:21], vcc
	v_cndmask_b32_e64 v80, v235, v80, s[38:39]
	v_mov_b32_e32 v81, v80
	s_nop 1
	v_permlane32_swap_b32_e32 v80, v81
	v_max_f32_e32 v80, v80, v81
	v_cmp_gt_f32_e32 vcc, v80, v78
	s_cbranch_vccz .LBB0_727
	v_max_f32_e32 v81, v78, v78
	v_max_f32_e32 v80, v81, v80
	v_sub_f32_e32 v78, v78, v80
	v_exp_f32_e32 v78, v78
	s_nop 0
	v_mul_f32_e32 v157, v157, v78
	v_pk_mul_f32 v[34:35], v[34:35], v[78:79] op_sel_hi:[1,0]
	v_pk_mul_f32 v[32:33], v[32:33], v[78:79] op_sel_hi:[1,0]
	v_pk_mul_f32 v[30:31], v[30:31], v[78:79] op_sel_hi:[1,0]
	v_pk_mul_f32 v[28:29], v[28:29], v[78:79] op_sel_hi:[1,0]
	v_pk_mul_f32 v[26:27], v[26:27], v[78:79] op_sel_hi:[1,0]
	v_pk_mul_f32 v[24:25], v[24:25], v[78:79] op_sel_hi:[1,0]
	v_pk_mul_f32 v[22:23], v[22:23], v[78:79] op_sel_hi:[1,0]
	v_pk_mul_f32 v[20:21], v[20:21], v[78:79] op_sel_hi:[1,0]
	v_pk_mul_f32 v[18:19], v[18:19], v[78:79] op_sel_hi:[1,0]
	v_pk_mul_f32 v[16:17], v[16:17], v[78:79] op_sel_hi:[1,0]
	v_pk_mul_f32 v[14:15], v[14:15], v[78:79] op_sel_hi:[1,0]
	v_pk_mul_f32 v[12:13], v[12:13], v[78:79] op_sel_hi:[1,0]
	v_pk_mul_f32 v[10:11], v[10:11], v[78:79] op_sel_hi:[1,0]
	v_pk_mul_f32 v[8:9], v[8:9], v[78:79] op_sel_hi:[1,0]
	v_pk_mul_f32 v[6:7], v[6:7], v[78:79] op_sel_hi:[1,0]
	v_pk_mul_f32 v[4:5], v[4:5], v[78:79] op_sel_hi:[1,0]
	v_mov_b32_e32 v78, v80

; __device__ __forceinline__ float half_max(float v) { unsigned a, b; half_swap(__builtin_bit_cast(unsigned, v), a, b); return fmaxf(__builtin_bit_cast(float, a), __builtin_bit_cast(float, b)); }
;     __device__ __forceinline__ void begin(int k0) { set_base((float)(tq - k0)); }
;     __device__ __forceinline__ void begin(int k0) { set_base((float)(tq - k0)); }
;     __device__ __forceinline__ void begin(int k0) { set_base((float)(tq - 31 - 16 * k0) * (1.f / 16.f)); }
;     __device__ __forceinline__ void begin(int k0) { set_base((float)(iq - k0)); }
;     __device__ __forceinline__ void begin(int k0) { set_base((float)(tq - k0)); }
; template <int NDT, class F>
; __device__ __forceinline__ void softmax_body(f32x16& s, const F& f, int k0, int hh, f32x16 (&o)[NDT], float& m, float& l, bf16x8& pf0, bf16x8& pf1, const int MASK) {
;     float mx = NEG_BIG;
;     if (MASK == 1) {
; #pragma unroll
;         for (int r = 0; r < 16; ++r) s[r] = f.valid(k0 + CR(r) + 4 * hh) ? s[r] : NEG_BIG; }
; #pragma unroll
;     for (int r = 0; r < 16; ++r) mx = fmaxf(mx, s[r]);
;     mx = fmaf(mx, QK_SCL, f.tadd);
;     const bool on = MASK != 2 || f.lane_on();
;     mx = on ? mx : NEG_BIG;
;     mx = half_max(mx);
;     if (__ballot(mx > m) != 0ull) { const float mn = fmaxf(m, mx), alpha = __builtin_amdgcn_exp2f(m - mn); m = mn; l *= alpha;
; #pragma unroll
;         for (int dt = 0; dt < NDT; ++dt) o[dt] = o[dt] * alpha; }
.LBB0_737:
	s_nop 10
	v_max3_f32 v111, v84, s86, v85
	v_max3_f32 v111, v111, v86, v87
	v_subrev_u32_e32 v110, s31, v116
	v_max3_f32 v111, v111, v88, v89
	v_cvt_f32_i32_e32 v110, v110
	v_max3_f32 v111, v111, v90, v91
	v_max3_f32 v111, v111, v92, v93
	v_max3_f32 v111, v111, v94, v95
	v_max3_f32 v111, v111, v96, v97
	v_mul_f32_e64 v110, -v1, v110
	v_max3_f32 v111, v111, v98, v99
	v_fmamk_f32 v111, v111, 0x3e38aa3b, v110
	v_mov_b32_e32 v112, v111
	s_nop 1
	v_permlane32_swap_b32_e32 v111, v112
	v_max_f32_e32 v111, v111, v112
	v_cmp_gt_f32_e32 vcc, v111, v109
	s_cbranch_vccz .LBB0_732
	v_max_f32_e32 v112, v109, v109
	v_max_f32_e32 v111, v112, v111
	v_sub_f32_e32 v109, v109, v111
	v_exp_f32_e32 v112, v109
	v_mov_b32_e32 v109, v111
	v_mul_f32_e32 v149, v149, v112
	v_pk_mul_f32 v[66:67], v[66:67], v[112:113] op_sel_hi:[1,0]
	v_pk_mul_f32 v[64:65], v[64:65], v[112:113] op_sel_hi:[1,0]
	v_pk_mul_f32 v[62:63], v[62:63], v[112:113] op_sel_hi:[1,0]
	v_pk_mul_f32 v[60:61], v[60:61], v[112:113] op_sel_hi:[1,0]
	v_pk_mul_f32 v[58:59], v[58:59], v[112:113] op_sel_hi:[1,0]
	v_pk_mul_f32 v[56:57], v[56:57], v[112:113] op_sel_hi:[1,0]
	v_pk_mul_f32 v[54:55], v[54:55], v[112:113] op_sel_hi:[1,0]
	v_pk_mul_f32 v[52:53], v[52:53], v[112:113] op_sel_hi:[1,0]
	v_pk_mul_f32 v[50:51], v[50:51], v[112:113] op_sel_hi:[1,0]
	v_pk_mul_f32 v[48:49], v[48:49], v[112:113] op_sel_hi:[1,0]
	v_pk_mul_f32 v[46:47], v[46:47], v[112:113] op_sel_hi:[1,0]
	v_pk_mul_f32 v[44:45], v[44:45], v[112:113] op_sel_hi:[1,0]
	v_pk_mul_f32 v[42:43], v[42:43], v[112:113] op_sel_hi:[1,0]
	v_pk_mul_f32 v[40:41], v[40:41], v[112:113] op_sel_hi:[1,0]
	v_pk_mul_f32 v[38:39], v[38:39], v[112:113] op_sel_hi:[1,0]
	v_pk_mul_f32 v[36:37], v[36:37], v[112:113] op_sel_hi:[1,0]
	s_branch .LBB0_732

; __device__ __forceinline__ float half_max(float v) { unsigned a, b; half_swap(__builtin_bit_cast(unsigned, v), a, b); return fmaxf(__builtin_bit_cast(float, a), __builtin_bit_cast(float, b)); }
;     __device__ __forceinline__ void begin(int k0) { set_base((float)(tq - k0)); }
;     __device__ __forceinline__ void begin(int k0) { set_base((float)(tq - k0)); }
;     __device__ __forceinline__ void begin(int k0) { set_base((float)(tq - k0)); }
;     __device__ __forceinline__ void begin(int k0) { set_base((float)(iq - k0)); }
;     __device__ __forceinline__ void begin(int k0) { set_base((float)(tq - 31 - 16 * k0) * (1.f / 16.f)); }
; template <int NDT, class F>
; __device__ __forceinline__ void softmax_body(f32x16& s, const F& f, int k0, int hh, f32x16 (&o)[NDT], float& m, float& l, bf16x8& pf0, bf16x8& pf1, const int MASK) {
;     float mx = NEG_BIG;
;     if (MASK == 1) {
; #pragma unroll
;         for (int r = 0; r < 16; ++r) s[r] = f.valid(k0 + CR(r) + 4 * hh) ? s[r] : NEG_BIG; }
; #pragma unroll
;     for (int r = 0; r < 16; ++r) mx = fmaxf(mx, s[r]);
;     mx = fmaf(mx, QK_SCL, f.tadd);
;     const bool on = MASK != 2 || f.lane_on();
;     mx = on ? mx : NEG_BIG;
;     mx = half_max(mx);
;     if (__ballot(mx > m) != 0ull) { const float mn = fmaxf(m, mx), alpha = __builtin_amdgcn_exp2f(m - mn); m = mn; l *= alpha;
; #pragma unroll
;         for (int dt = 0; dt < NDT; ++dt) o[dt] = o[dt] * alpha; }
.LBB0_747:
	s_lshl_b32 s23, s23, 9
	s_nop 9
	v_max3_f32 v175, v116, s86, v117
	v_subrev_u32_e32 v174, s23, v151
	v_max3_f32 v175, v175, v118, v119
	v_cvt_f32_i32_e32 v174, v174
	v_max3_f32 v175, v175, v120, v121
	v_max3_f32 v175, v175, v122, v123
	v_max3_f32 v175, v175, v124, v125
	v_max3_f32 v175, v175, v126, v127
	v_mul_f32_e32 v174, 0xbd800000, v174
	v_max3_f32 v175, v175, v128, v129
	v_mul_f32_e32 v174, v174, v162
	v_max3_f32 v175, v175, v130, v131
	v_fmamk_f32 v175, v175, 0x3e38aa3b, v174
	v_mov_b32_e32 v176, v175
	s_nop 1
	v_permlane32_swap_b32_e32 v175, v176
	v_max_f32_e32 v175, v175, v176
	v_cmp_gt_f32_e32 vcc, v175, v173
	s_cbranch_vccz .LBB0_742
	v_max_f32_e32 v176, v173, v173
	v_max_f32_e32 v175, v176, v175
	v_sub_f32_e32 v173, v173, v175
	v_exp_f32_e32 v176, v173
	v_mov_b32_e32 v173, v175
	v_mul_f32_e32 v156, v156, v176
	v_pk_mul_f32 v[82:83], v[82:83], v[176:177] op_sel_hi:[1,0]
	v_pk_mul_f32 v[80:81], v[80:81], v[176:177] op_sel_hi:[1,0]
	v_pk_mul_f32 v[78:79], v[78:79], v[176:177] op_sel_hi:[1,0]
	v_pk_mul_f32 v[76:77], v[76:77], v[176:177] op_sel_hi:[1,0]
	v_pk_mul_f32 v[74:75], v[74:75], v[176:177] op_sel_hi:[1,0]
	v_pk_mul_f32 v[72:73], v[72:73], v[176:177] op_sel_hi:[1,0]
	v_pk_mul_f32 v[70:71], v[70:71], v[176:177] op_sel_hi:[1,0]
	v_pk_mul_f32 v[68:69], v[68:69], v[176:177] op_sel_hi:[1,0]
	v_pk_mul_f32 v[98:99], v[98:99], v[176:177] op_sel_hi:[1,0]
	v_pk_mul_f32 v[96:97], v[96:97], v[176:177] op_sel_hi:[1,0]
	v_pk_mul_f32 v[94:95], v[94:95], v[176:177] op_sel_hi:[1,0]
	v_pk_mul_f32 v[92:93], v[92:93], v[176:177] op_sel_hi:[1,0]
	v_pk_mul_f32 v[90:91], v[90:91], v[176:177] op_sel_hi:[1,0]
	v_pk_mul_f32 v[88:89], v[88:89], v[176:177] op_sel_hi:[1,0]
	v_pk_mul_f32 v[86:87], v[86:87], v[176:177] op_sel_hi:[1,0]
	v_pk_mul_f32 v[84:85], v[84:85], v[176:177] op_sel_hi:[1,0]
	s_branch .LBB0_742

; __device__ __forceinline__ float half_max(float v) { unsigned a, b; half_swap(__builtin_bit_cast(unsigned, v), a, b); return fmaxf(__builtin_bit_cast(float, a), __builtin_bit_cast(float, b)); }
;     __device__ __forceinline__ void begin(int k0) { set_base((float)(tq - k0)); }
;     __device__ __forceinline__ void begin(int k0) { set_base((float)(tq - k0)); }
;     __device__ __forceinline__ void begin(int k0) { set_base((float)(tq - k0)); }
;     __device__ __forceinline__ void begin(int k0) { set_base((float)(tq - 31 - 16 * k0) * (1.f / 16.f)); }
;     __device__ __forceinline__ void begin(int k0) { set_base((float)(iq - k0)); }
; template <int NDT, class F>
; __device__ __forceinline__ void softmax_body(f32x16& s, const F& f, int k0, int hh, f32x16 (&o)[NDT], float& m, float& l, bf16x8& pf0, bf16x8& pf1, const int MASK) {
;     float mx = NEG_BIG;
;     if (MASK == 1) {
; #pragma unroll
;         for (int r = 0; r < 16; ++r) s[r] = f.valid(k0 + CR(r) + 4 * hh) ? s[r] : NEG_BIG; }
; #pragma unroll
;     for (int r = 0; r < 16; ++r) mx = fmaxf(mx, s[r]);
;     mx = fmaf(mx, QK_SCL, f.tadd);
;     const bool on = MASK != 2 || f.lane_on();
;     mx = on ? mx : NEG_BIG;
;     mx = half_max(mx);
;     if (__ballot(mx > m) != 0ull) { const float mn = fmaxf(m, mx), alpha = __builtin_amdgcn_exp2f(m - mn); m = mn; l *= alpha;
; #pragma unroll
;         for (int dt = 0; dt < NDT; ++dt) o[dt] = o[dt] * alpha; }
.LBB0_779:
.LBB0_780:
	s_lshl_b32 s30, s30, 5
	v_subrev_u32_e32 v102, s30, v136
	v_cvt_f32_i32_e32 v102, v102
	v_add_u32_e32 v105, s30, v166
	v_cmp_le_i32_e32 vcc, v105, v136
	v_cmp_gt_i32_e64 s[40:41], v105, v112
	v_mul_f32_e64 v104, -v108, v102
	s_and_b64 vcc, vcc, s[40:41]
	v_sub_u32_e32 v102, v105, v136
	v_cndmask_b32_e32 v68, v235, v68, vcc
	v_cmp_lt_i32_e32 vcc, v105, v136
	v_cmp_lt_i32_e64 s[40:41], s91, v102
	s_and_b64 vcc, vcc, s[40:41]
	v_or_b32_e32 v102, 2, v105
	v_cndmask_b32_e32 v69, v235, v69, vcc
	v_cmp_le_i32_e32 vcc, v102, v136
	v_cmp_gt_i32_e64 s[40:41], v102, v112
	s_and_b64 vcc, vcc, s[40:41]
	v_or_b32_e32 v102, 3, v105
	v_cndmask_b32_e32 v70, v235, v70, vcc
	v_cmp_le_i32_e32 vcc, v102, v136
	v_cmp_gt_i32_e64 s[40:41], v102, v112
	s_and_b64 vcc, vcc, s[40:41]
	v_add_u32_e32 v102, 8, v105
	v_cndmask_b32_e32 v71, v235, v71, vcc
	v_cmp_le_i32_e32 vcc, v102, v136
	v_cmp_gt_i32_e64 s[40:41], v102, v112
	s_and_b64 vcc, vcc, s[40:41]
	v_cndmask_b32_e32 v102, v235, v72, vcc
	v_add_u32_e32 v72, 9, v105
	v_cmp_le_i32_e32 vcc, v72, v136
	v_cmp_gt_i32_e64 s[40:41], v72, v112
	s_and_b64 vcc, vcc, s[40:41]
	v_add_u32_e32 v72, 10, v105
	v_cndmask_b32_e32 v103, v235, v73, vcc
	v_cmp_le_i32_e32 vcc, v72, v136
	v_cmp_gt_i32_e64 s[40:41], v72, v112
	s_and_b64 vcc, vcc, s[40:41]
	v_add_u32_e32 v72, 11, v105
	v_cndmask_b32_e32 v74, v235, v74, vcc
	v_cmp_le_i32_e32 vcc, v72, v136
	v_cmp_gt_i32_e64 s[40:41], v72, v112
	s_and_b64 vcc, vcc, s[40:41]
	v_add_u32_e32 v72, 16, v105
	v_cndmask_b32_e32 v75, v235, v75, vcc
	v_cmp_le_i32_e32 vcc, v72, v136
	v_cmp_gt_i32_e64 s[40:41], v72, v112
	s_and_b64 vcc, vcc, s[40:41]
	v_add_u32_e32 v72, 17, v105
	v_cndmask_b32_e32 v76, v235, v76, vcc
	v_cmp_le_i32_e32 vcc, v72, v136
	v_cmp_gt_i32_e64 s[40:41], v72, v112
	s_and_b64 vcc, vcc, s[40:41]
	v_add_u32_e32 v72, 18, v105
	v_cndmask_b32_e32 v77, v235, v77, vcc
	v_cmp_le_i32_e32 vcc, v72, v136
	v_cmp_gt_i32_e64 s[40:41], v72, v112
	s_and_b64 vcc, vcc, s[40:41]
	v_add_u32_e32 v72, 19, v105
	v_cndmask_b32_e32 v78, v235, v78, vcc
	v_cmp_le_i32_e32 vcc, v72, v136
	v_cmp_gt_i32_e64 s[40:41], v72, v112
	s_and_b64 vcc, vcc, s[40:41]
	v_add_u32_e32 v72, 24, v105
	v_cndmask_b32_e32 v79, v235, v79, vcc
	v_cmp_le_i32_e32 vcc, v72, v136
	v_cmp_gt_i32_e64 s[40:41], v72, v112
	s_and_b64 vcc, vcc, s[40:41]
	v_add_u32_e32 v72, 25, v105
	v_cndmask_b32_e32 v80, v235, v80, vcc
	v_cmp_le_i32_e32 vcc, v72, v136
	v_cmp_gt_i32_e64 s[40:41], v72, v112
	s_and_b64 vcc, vcc, s[40:41]
	v_add_u32_e32 v72, 26, v105
	v_cndmask_b32_e32 v81, v235, v81, vcc
	v_cmp_le_i32_e32 vcc, v72, v136
	v_cmp_gt_i32_e64 s[40:41], v72, v112
	s_and_b64 vcc, vcc, s[40:41]
	v_cndmask_b32_e32 v72, v235, v82, vcc
	v_max3_f32 v82, v68, s86, v69
	v_max3_f32 v82, v82, v70, v71
	v_max3_f32 v82, v82, v102, v103
	v_add_u32_e32 v73, 27, v105
	v_max3_f32 v82, v82, v74, v75
	v_cmp_le_i32_e32 vcc, v73, v136
	v_cmp_gt_i32_e64 s[40:41], v73, v112
	v_max3_f32 v82, v82, v76, v77
	s_and_b64 vcc, vcc, s[40:41]
	v_max3_f32 v82, v82, v78, v79
	v_cndmask_b32_e32 v73, v235, v83, vcc
	v_max3_f32 v82, v82, v80, v81
	v_max3_f32 v82, v82, v72, v73
	v_fmamk_f32 v82, v82, 0x3e38aa3b, v104
	v_mov_b32_e32 v83, v82
	s_nop 1
	v_permlane32_swap_b32_e32 v82, v83
	v_max_f32_e32 v82, v82, v83
	v_cmp_gt_f32_e32 vcc, v82, v1
	s_cbranch_vccz .LBB0_782
	v_max_f32_e32 v83, v1, v1
	v_max_f32_e32 v83, v83, v82
	v_sub_f32_e32 v1, v1, v83
	v_exp_f32_e32 v82, v1
	v_mov_b32_e32 v1, v83
	v_mul_f32_e32 v168, v168, v82
	v_pk_mul_f32 v[34:35], v[34:35], v[82:83] op_sel_hi:[1,0]
	v_pk_mul_f32 v[32:33], v[32:33], v[82:83] op_sel_hi:[1,0]
	v_pk_mul_f32 v[30:31], v[30:31], v[82:83] op_sel_hi:[1,0]
	v_pk_mul_f32 v[28:29], v[28:29], v[82:83] op_sel_hi:[1,0]
	v_pk_mul_f32 v[26:27], v[26:27], v[82:83] op_sel_hi:[1,0]
	v_pk_mul_f32 v[24:25], v[24:25], v[82:83] op_sel_hi:[1,0]
	v_pk_mul_f32 v[22:23], v[22:23], v[82:83] op_sel_hi:[1,0]
	v_pk_mul_f32 v[20:21], v[20:21], v[82:83] op_sel_hi:[1,0]
	v_pk_mul_f32 v[18:19], v[18:19], v[82:83] op_sel_hi:[1,0]
	v_pk_mul_f32 v[16:17], v[16:17], v[82:83] op_sel_hi:[1,0]
	v_pk_mul_f32 v[14:15], v[14:15], v[82:83] op_sel_hi:[1,0]
	v_pk_mul_f32 v[12:13], v[12:13], v[82:83] op_sel_hi:[1,0]
	v_pk_mul_f32 v[10:11], v[10:11], v[82:83] op_sel_hi:[1,0]
	v_pk_mul_f32 v[8:9], v[8:9], v[82:83] op_sel_hi:[1,0]
	v_pk_mul_f32 v[6:7], v[6:7], v[82:83] op_sel_hi:[1,0]
	v_pk_mul_f32 v[4:5], v[4:5], v[82:83] op_sel_hi:[1,0]

; __device__ __forceinline__ float half_max(float v) { unsigned a, b; half_swap(__builtin_bit_cast(unsigned, v), a, b); return fmaxf(__builtin_bit_cast(float, a), __builtin_bit_cast(float, b)); }
;     __device__ __forceinline__ void begin(int k0) { set_base((float)(tq - k0)); }
;     __device__ __forceinline__ void begin(int k0) { set_base((float)(tq - k0)); }
;     __device__ __forceinline__ void begin(int k0) { set_base((float)(tq - k0)); }
;     __device__ __forceinline__ void begin(int k0) { set_base((float)(tq - 31 - 16 * k0) * (1.f / 16.f)); }
;     __device__ __forceinline__ void begin(int k0) { set_base((float)(iq - k0)); }
; template <int NDT, class F>
; __device__ __forceinline__ void softmax_body(f32x16& s, const F& f, int k0, int hh, f32x16 (&o)[NDT], float& m, float& l, bf16x8& pf0, bf16x8& pf1, const int MASK) {
;     float mx = NEG_BIG;
;     if (MASK == 1) {
; #pragma unroll
;         for (int r = 0; r < 16; ++r) s[r] = f.valid(k0 + CR(r) + 4 * hh) ? s[r] : NEG_BIG; }
; #pragma unroll
;     for (int r = 0; r < 16; ++r) mx = fmaxf(mx, s[r]);
;     mx = fmaf(mx, QK_SCL, f.tadd);
;     const bool on = MASK != 2 || f.lane_on();
;     mx = on ? mx : NEG_BIG;
;     mx = half_max(mx);
;     if (__ballot(mx > m) != 0ull) { const float mn = fmaxf(m, mx), alpha = __builtin_amdgcn_exp2f(m - mn); m = mn; l *= alpha;
; #pragma unroll
;         for (int dt = 0; dt < NDT; ++dt) o[dt] = o[dt] * alpha; }
.LBB0_818:
.LBB0_819:
	s_lshl_b32 s24, s30, 5
	v_subrev_u32_e32 v136, s24, v145
	v_cvt_f32_i32_e32 v136, v136
	v_add_u32_e32 v139, s24, v166
	v_cmp_le_i32_e32 vcc, v139, v145
	v_cmp_gt_i32_e64 s[40:41], v139, v148
	v_mul_f32_e64 v138, -v143, v136
	s_and_b64 vcc, vcc, s[40:41]
	v_sub_u32_e32 v136, v139, v145
	v_cndmask_b32_e32 v100, v235, v100, vcc
	v_cmp_lt_i32_e32 vcc, v139, v145
	v_cmp_lt_i32_e64 s[40:41], s91, v136
	s_and_b64 vcc, vcc, s[40:41]
	v_or_b32_e32 v136, 2, v139
	v_cndmask_b32_e32 v101, v235, v101, vcc
	v_cmp_le_i32_e32 vcc, v136, v145
	v_cmp_gt_i32_e64 s[40:41], v136, v148
	s_and_b64 vcc, vcc, s[40:41]
	v_or_b32_e32 v136, 3, v139
	v_cndmask_b32_e32 v102, v235, v102, vcc
	v_cmp_le_i32_e32 vcc, v136, v145
	v_cmp_gt_i32_e64 s[40:41], v136, v148
	s_and_b64 vcc, vcc, s[40:41]
	v_add_u32_e32 v136, 8, v139
	v_cndmask_b32_e32 v103, v235, v103, vcc
	v_cmp_le_i32_e32 vcc, v136, v145
	v_cmp_gt_i32_e64 s[40:41], v136, v148
	s_and_b64 vcc, vcc, s[40:41]
	v_cndmask_b32_e32 v136, v235, v104, vcc
	v_add_u32_e32 v104, 9, v139
	v_cmp_le_i32_e32 vcc, v104, v145
	v_cmp_gt_i32_e64 s[40:41], v104, v148
	s_and_b64 vcc, vcc, s[40:41]
	v_add_u32_e32 v104, 10, v139
	v_cndmask_b32_e32 v137, v235, v105, vcc
	v_cmp_le_i32_e32 vcc, v104, v145
	v_cmp_gt_i32_e64 s[40:41], v104, v148
	s_and_b64 vcc, vcc, s[40:41]
	v_add_u32_e32 v104, 11, v139
	v_cndmask_b32_e32 v106, v235, v106, vcc
	v_cmp_le_i32_e32 vcc, v104, v145
	v_cmp_gt_i32_e64 s[40:41], v104, v148
	s_and_b64 vcc, vcc, s[40:41]
	v_add_u32_e32 v104, 16, v139
	v_cndmask_b32_e32 v107, v235, v107, vcc
	v_cmp_le_i32_e32 vcc, v104, v145
	v_cmp_gt_i32_e64 s[40:41], v104, v148
	s_and_b64 vcc, vcc, s[40:41]
	v_add_u32_e32 v104, 17, v139
	v_cndmask_b32_e32 v108, v235, v108, vcc
	v_cmp_le_i32_e32 vcc, v104, v145
	v_cmp_gt_i32_e64 s[40:41], v104, v148
	s_and_b64 vcc, vcc, s[40:41]
	v_add_u32_e32 v104, 18, v139
	v_cndmask_b32_e32 v109, v235, v109, vcc
	v_cmp_le_i32_e32 vcc, v104, v145
	v_cmp_gt_i32_e64 s[40:41], v104, v148
	s_and_b64 vcc, vcc, s[40:41]
	v_add_u32_e32 v104, 19, v139
	v_cndmask_b32_e32 v110, v235, v110, vcc
	v_cmp_le_i32_e32 vcc, v104, v145
	v_cmp_gt_i32_e64 s[40:41], v104, v148
	s_and_b64 vcc, vcc, s[40:41]
	v_add_u32_e32 v104, 24, v139
	v_cndmask_b32_e32 v111, v235, v111, vcc
	v_cmp_le_i32_e32 vcc, v104, v145
	v_cmp_gt_i32_e64 s[40:41], v104, v148
	s_and_b64 vcc, vcc, s[40:41]
	v_add_u32_e32 v104, 25, v139
	v_cndmask_b32_e32 v112, v235, v112, vcc
	v_cmp_le_i32_e32 vcc, v104, v145
	v_cmp_gt_i32_e64 s[40:41], v104, v148
	s_and_b64 vcc, vcc, s[40:41]
	v_add_u32_e32 v104, 26, v139
	v_cndmask_b32_e32 v113, v235, v113, vcc
	v_cmp_le_i32_e32 vcc, v104, v145
	v_cmp_gt_i32_e64 s[40:41], v104, v148
	s_and_b64 vcc, vcc, s[40:41]
	v_cndmask_b32_e32 v104, v235, v114, vcc
	v_max3_f32 v114, v100, s86, v101
	v_max3_f32 v114, v114, v102, v103
	v_max3_f32 v114, v114, v136, v137
	v_add_u32_e32 v105, 27, v139
	v_max3_f32 v114, v114, v106, v107
	v_cmp_le_i32_e32 vcc, v105, v145
	v_cmp_gt_i32_e64 s[40:41], v105, v148
	v_max3_f32 v114, v114, v108, v109
	s_and_b64 vcc, vcc, s[40:41]
	v_max3_f32 v114, v114, v110, v111
	v_cndmask_b32_e32 v105, v235, v115, vcc
	v_max3_f32 v114, v114, v112, v113
	v_max3_f32 v114, v114, v104, v105
	v_fmamk_f32 v114, v114, 0x3e38aa3b, v138
	v_mov_b32_e32 v115, v114
	s_nop 1
	v_permlane32_swap_b32_e32 v114, v115
	v_max_f32_e32 v114, v114, v115
	v_cmp_gt_f32_e32 vcc, v114, v180
	s_cbranch_vccz .LBB0_821
	v_max_f32_e32 v115, v180, v180
	v_max_f32_e32 v115, v115, v114
	v_sub_f32_e32 v114, v180, v115
	v_exp_f32_e32 v114, v114
	v_mov_b32_e32 v180, v115
	v_mul_f32_e32 v171, v171, v114
	v_pk_mul_f32 v[66:67], v[66:67], v[114:115] op_sel_hi:[1,0]
	v_pk_mul_f32 v[64:65], v[64:65], v[114:115] op_sel_hi:[1,0]
	v_pk_mul_f32 v[62:63], v[62:63], v[114:115] op_sel_hi:[1,0]
	v_pk_mul_f32 v[60:61], v[60:61], v[114:115] op_sel_hi:[1,0]
	v_pk_mul_f32 v[58:59], v[58:59], v[114:115] op_sel_hi:[1,0]
	v_pk_mul_f32 v[56:57], v[56:57], v[114:115] op_sel_hi:[1,0]
	v_pk_mul_f32 v[54:55], v[54:55], v[114:115] op_sel_hi:[1,0]
	v_pk_mul_f32 v[52:53], v[52:53], v[114:115] op_sel_hi:[1,0]
	v_pk_mul_f32 v[50:51], v[50:51], v[114:115] op_sel_hi:[1,0]
	v_pk_mul_f32 v[48:49], v[48:49], v[114:115] op_sel_hi:[1,0]
	v_pk_mul_f32 v[46:47], v[46:47], v[114:115] op_sel_hi:[1,0]
	v_pk_mul_f32 v[44:45], v[44:45], v[114:115] op_sel_hi:[1,0]
	v_pk_mul_f32 v[42:43], v[42:43], v[114:115] op_sel_hi:[1,0]
	v_pk_mul_f32 v[40:41], v[40:41], v[114:115] op_sel_hi:[1,0]
	v_pk_mul_f32 v[38:39], v[38:39], v[114:115] op_sel_hi:[1,0]
	v_pk_mul_f32 v[36:37], v[36:37], v[114:115] op_sel_hi:[1,0]

; __device__ __forceinline__ float half_max(float v) { unsigned a, b; half_swap(__builtin_bit_cast(unsigned, v), a, b); return fmaxf(__builtin_bit_cast(float, a), __builtin_bit_cast(float, b)); }
;     __device__ __forceinline__ void begin(int k0) { set_base((float)(tq - k0)); }
;     __device__ __forceinline__ void begin(int k0) { set_base((float)(tq - k0)); }
;     __device__ __forceinline__ void begin(int k0) { set_base((float)(tq - k0)); }
;     __device__ __forceinline__ void begin(int k0) { set_base((float)(tq - 31 - 16 * k0) * (1.f / 16.f)); }
;     __device__ __forceinline__ void begin(int k0) { set_base((float)(iq - k0)); }
; template <int NDT, class F>
; __device__ __forceinline__ void softmax_body(f32x16& s, const F& f, int k0, int hh, f32x16 (&o)[NDT], float& m, float& l, bf16x8& pf0, bf16x8& pf1, const int MASK) {
;     float mx = NEG_BIG;
;     if (MASK == 1) {
; #pragma unroll
;         for (int r = 0; r < 16; ++r) s[r] = f.valid(k0 + CR(r) + 4 * hh) ? s[r] : NEG_BIG; }
; #pragma unroll
;     for (int r = 0; r < 16; ++r) mx = fmaxf(mx, s[r]);
;     mx = fmaf(mx, QK_SCL, f.tadd);
;     const bool on = MASK != 2 || f.lane_on();
;     mx = on ? mx : NEG_BIG;
;     mx = half_max(mx);
;     if (__ballot(mx > m) != 0ull) { const float mn = fmaxf(m, mx), alpha = __builtin_amdgcn_exp2f(m - mn); m = mn; l *= alpha;
; #pragma unroll
;         for (int dt = 0; dt < NDT; ++dt) o[dt] = o[dt] * alpha; }
.LBB0_857:
.LBB0_858:
	s_lshl_b32 s20, s23, 5
	v_subrev_u32_e32 v174, s20, v184
	v_cvt_f32_i32_e32 v174, v174
	v_add_u32_e32 v177, s20, v166
	v_cmp_le_i32_e32 vcc, v177, v184
	v_cmp_gt_i32_e64 s[40:41], v177, v187
	v_mul_f32_e64 v176, -v182, v174
	s_and_b64 vcc, vcc, s[40:41]
	v_sub_u32_e32 v174, v177, v184
	v_cndmask_b32_e32 v132, v235, v132, vcc
	v_cmp_lt_i32_e32 vcc, v177, v184
	v_cmp_lt_i32_e64 s[40:41], s91, v174
	s_and_b64 vcc, vcc, s[40:41]
	v_or_b32_e32 v174, 2, v177
	v_cndmask_b32_e32 v133, v235, v133, vcc
	v_cmp_le_i32_e32 vcc, v174, v184
	v_cmp_gt_i32_e64 s[40:41], v174, v187
	s_and_b64 vcc, vcc, s[40:41]
	v_or_b32_e32 v174, 3, v177
	v_cndmask_b32_e32 v134, v235, v134, vcc
	v_cmp_le_i32_e32 vcc, v174, v184
	v_cmp_gt_i32_e64 s[40:41], v174, v187
	s_and_b64 vcc, vcc, s[40:41]
	v_add_u32_e32 v174, 8, v177
	v_cndmask_b32_e32 v135, v235, v135, vcc
	v_cmp_le_i32_e32 vcc, v174, v184
	v_cmp_gt_i32_e64 s[40:41], v174, v187
	s_and_b64 vcc, vcc, s[40:41]
	v_cndmask_b32_e32 v174, v235, v136, vcc
	v_add_u32_e32 v136, 9, v177
	v_cmp_le_i32_e32 vcc, v136, v184
	v_cmp_gt_i32_e64 s[40:41], v136, v187
	s_and_b64 vcc, vcc, s[40:41]
	v_add_u32_e32 v136, 10, v177
	v_cndmask_b32_e32 v175, v235, v137, vcc
	v_cmp_le_i32_e32 vcc, v136, v184
	v_cmp_gt_i32_e64 s[40:41], v136, v187
	s_and_b64 vcc, vcc, s[40:41]
	v_add_u32_e32 v136, 11, v177
	v_cndmask_b32_e32 v138, v235, v138, vcc
	v_cmp_le_i32_e32 vcc, v136, v184
	v_cmp_gt_i32_e64 s[40:41], v136, v187
	s_and_b64 vcc, vcc, s[40:41]
	v_add_u32_e32 v136, 16, v177
	v_cndmask_b32_e32 v139, v235, v139, vcc
	v_cmp_le_i32_e32 vcc, v136, v184
	v_cmp_gt_i32_e64 s[40:41], v136, v187
	s_and_b64 vcc, vcc, s[40:41]
	v_add_u32_e32 v136, 17, v177
	v_cndmask_b32_e32 v140, v235, v140, vcc
	v_cmp_le_i32_e32 vcc, v136, v184
	v_cmp_gt_i32_e64 s[40:41], v136, v187
	s_and_b64 vcc, vcc, s[40:41]
	v_add_u32_e32 v136, 18, v177
	v_cndmask_b32_e32 v141, v235, v141, vcc
	v_cmp_le_i32_e32 vcc, v136, v184
	v_cmp_gt_i32_e64 s[40:41], v136, v187
	s_and_b64 vcc, vcc, s[40:41]
	v_add_u32_e32 v136, 19, v177
	v_cndmask_b32_e32 v142, v235, v142, vcc
	v_cmp_le_i32_e32 vcc, v136, v184
	v_cmp_gt_i32_e64 s[40:41], v136, v187
	s_and_b64 vcc, vcc, s[40:41]
	v_add_u32_e32 v136, 24, v177
	v_cndmask_b32_e32 v143, v235, v143, vcc
	v_cmp_le_i32_e32 vcc, v136, v184
	v_cmp_gt_i32_e64 s[40:41], v136, v187
	s_and_b64 vcc, vcc, s[40:41]
	v_add_u32_e32 v136, 25, v177
	v_cndmask_b32_e32 v144, v235, v144, vcc
	v_cmp_le_i32_e32 vcc, v136, v184
	v_cmp_gt_i32_e64 s[40:41], v136, v187
	s_and_b64 vcc, vcc, s[40:41]
	v_add_u32_e32 v136, 26, v177
	v_cndmask_b32_e32 v145, v235, v145, vcc
	v_cmp_le_i32_e32 vcc, v136, v184
	v_cmp_gt_i32_e64 s[40:41], v136, v187
	s_and_b64 vcc, vcc, s[40:41]
	v_cndmask_b32_e32 v136, v235, v146, vcc
	v_max3_f32 v146, v132, s86, v133
	v_max3_f32 v146, v146, v134, v135
	v_max3_f32 v146, v146, v174, v175
	v_add_u32_e32 v137, 27, v177
	v_max3_f32 v146, v146, v138, v139
	v_cmp_le_i32_e32 vcc, v137, v184
	v_cmp_gt_i32_e64 s[40:41], v137, v187
	v_max3_f32 v146, v146, v140, v141
	s_and_b64 vcc, vcc, s[40:41]
	v_max3_f32 v146, v146, v142, v143
	v_cndmask_b32_e32 v137, v235, v147, vcc
	v_max3_f32 v146, v146, v144, v145
	v_max3_f32 v146, v146, v136, v137
	v_fmamk_f32 v146, v146, 0x3e38aa3b, v176
	v_mov_b32_e32 v147, v146
	s_nop 1
	v_permlane32_swap_b32_e32 v146, v147
	v_max_f32_e32 v146, v146, v147
	v_cmp_gt_f32_e32 vcc, v146, v167
	s_cbranch_vccz .LBB0_860
	v_max_f32_e32 v147, v167, v167
	v_max_f32_e32 v147, v147, v146
	v_sub_f32_e32 v146, v167, v147
	v_exp_f32_e32 v146, v146
	v_mov_b32_e32 v167, v147
	v_mul_f32_e32 v169, v169, v146
	v_pk_mul_f32 v[98:99], v[98:99], v[146:147] op_sel_hi:[1,0]
	v_pk_mul_f32 v[96:97], v[96:97], v[146:147] op_sel_hi:[1,0]
	v_pk_mul_f32 v[94:95], v[94:95], v[146:147] op_sel_hi:[1,0]
	v_pk_mul_f32 v[92:93], v[92:93], v[146:147] op_sel_hi:[1,0]
	v_pk_mul_f32 v[90:91], v[90:91], v[146:147] op_sel_hi:[1,0]
	v_pk_mul_f32 v[88:89], v[88:89], v[146:147] op_sel_hi:[1,0]
	v_pk_mul_f32 v[86:87], v[86:87], v[146:147] op_sel_hi:[1,0]
	v_pk_mul_f32 v[84:85], v[84:85], v[146:147] op_sel_hi:[1,0]
	v_pk_mul_f32 v[82:83], v[82:83], v[146:147] op_sel_hi:[1,0]
	v_pk_mul_f32 v[80:81], v[80:81], v[146:147] op_sel_hi:[1,0]
	v_pk_mul_f32 v[78:79], v[78:79], v[146:147] op_sel_hi:[1,0]
	v_pk_mul_f32 v[76:77], v[76:77], v[146:147] op_sel_hi:[1,0]
	v_pk_mul_f32 v[74:75], v[74:75], v[146:147] op_sel_hi:[1,0]
	v_pk_mul_f32 v[72:73], v[72:73], v[146:147] op_sel_hi:[1,0]
	v_pk_mul_f32 v[70:71], v[70:71], v[146:147] op_sel_hi:[1,0]
	v_pk_mul_f32 v[68:69], v[68:69], v[146:147] op_sel_hi:[1,0]
